# plus FoX K/V tile prefetch addresses from SGPR base + 32-bit lane offset (16 fewer VALU per tile)
# speedup vs baseline: 1.0075x; 1.0055x over previous
.LBB0_646:
	v_mul_lo_u32 v157, v146, s45
	v_lshlrev_b32_e32 v158, 4, v0
	v_add3_u32 v0, 0, v157, v158
	s_waitcnt vmcnt(0)
	ds_write_b128 v0, v[14:17]
	v_mad_u64_u32 v[14:15], s[4:5], v146, 48, v[0:1]
	ds_write_b128 v14, v[10:13] offset:34816
	v_lshlrev_b64 v[10:11], 14, v[146:147]
	v_lshl_add_u64 v[10:11], s[20:21], 0, v[10:11]
	v_lshlrev_b64 v[12:13], 1, v[20:21]
	v_lshl_add_u64 v[10:11], v[10:11], 0, v[12:13]
	v_add_co_u32_e32 v10, vcc, s47, v10
	v_lshlrev_b64 v[14:15], 1, v[22:23]
	s_nop 0
	v_addc_co_u32_e32 v11, vcc, 0, v11, vcc
	global_load_dwordx4 v[130:133], v[10:11], off offset:-4096
	global_load_dwordx4 v[134:137], v[10:11], off
	v_lshlrev_b64 v[10:11], 14, v[148:149]
	v_lshl_add_u64 v[10:11], s[20:21], 0, v[10:11]
	v_lshl_add_u64 v[10:11], v[10:11], 0, v[14:15]
	v_add_co_u32_e32 v10, vcc, s47, v10
	v_mul_lo_u32 v160, v148, s45
	s_nop 0
	v_addc_co_u32_e32 v11, vcc, 0, v11, vcc
	global_load_dwordx4 v[138:141], v[10:11], off offset:-4096
	global_load_dwordx4 v[142:145], v[10:11], off
	v_lshlrev_b32_e32 v161, 4, v32
	v_add3_u32 v0, 0, v160, v161
	ds_write_b128 v0, v[2:5]
	v_mad_u64_u32 v[2:3], s[4:5], v148, 48, v[0:1]
	v_lshrrev_b32_e32 v0, 2, v18
	v_lshlrev_b32_e32 v163, 2, v31
	ds_write_b128 v2, v[6:9] offset:34816
	v_and_or_b32 v0, v0, 3, v163
	v_lshlrev_b32_e32 v2, 1, v18
	v_lshlrev_b32_e32 v3, 3, v18
	s_add_i32 s5, s33, s60
	v_lshl_add_u32 v149, v31, 4, 0
	v_mad_u32_u24 v0, v0, s46, 0
	v_and_b32_e32 v2, 32, v2
	v_and_b32_e32 v3, 24, v3
	v_lshl_add_u32 v152, v148, 14, v14
	v_mov_b32_e32 v14, v1
	v_mov_b32_e32 v15, v1
	v_mad_u32_u24 v162, v30, s45, v149
	v_add3_u32 v164, v0, v2, v3
	v_lshl_add_u32 v150, v146, 14, v12
	s_mov_b64 s[78:79], s[20:21]
	v_add_u32_e32 v195, s5, v30
	v_mov_b32_e32 v0, v1
	v_mov_b32_e32 v2, v1
	v_mov_b32_e32 v3, v1
	v_mov_b32_e32 v4, v1
	v_mov_b32_e32 v5, v1
	v_mov_b32_e32 v6, v1
	v_mov_b32_e32 v7, v1
	v_mov_b32_e32 v8, v1
	v_mov_b32_e32 v9, v1
	v_mov_b32_e32 v10, v1
	v_mov_b32_e32 v11, v1
	v_mov_b32_e32 v12, v1
	v_mov_b32_e32 v13, v1
	v_mov_b64_e32 v[64:65], v[14:15]
	v_mov_b64_e32 v[48:49], v[14:15]
	v_mov_b64_e32 v[32:33], v[14:15]
	s_lshl_b32 s6, s51, 2
	s_lshl_b32 s7, s51, 10
	v_mov_b64_e32 v[62:63], v[12:13]
	v_mov_b64_e32 v[60:61], v[10:11]
	v_mov_b64_e32 v[58:59], v[8:9]
	v_mov_b64_e32 v[56:57], v[6:7]
	v_mov_b64_e32 v[54:55], v[4:5]
	v_mov_b64_e32 v[52:53], v[2:3]
	v_mov_b64_e32 v[50:51], v[0:1]
	v_mov_b64_e32 v[46:47], v[12:13]
	v_mov_b64_e32 v[44:45], v[10:11]
	v_mov_b64_e32 v[42:43], v[8:9]
	v_mov_b64_e32 v[40:41], v[6:7]
	v_mov_b64_e32 v[38:39], v[4:5]
	v_mov_b64_e32 v[36:37], v[2:3]
	v_mov_b64_e32 v[34:35], v[0:1]
	v_mov_b64_e32 v[30:31], v[12:13]
	v_mov_b64_e32 v[28:29], v[10:11]
	v_mov_b64_e32 v[26:27], v[8:9]
	v_mov_b64_e32 v[24:25], v[6:7]
	v_mov_b64_e32 v[22:23], v[4:5]
	v_mov_b64_e32 v[20:21], v[2:3]
	v_mov_b64_e32 v[18:19], v[0:1]
	v_mov_b64_e32 v[16:17], v[14:15]
	s_mov_b32 s0, 2
	s_add_i32 s1, s6, 4
	v_mul_lo_u32 v159, v146, s46
	v_mul_lo_u32 v147, v148, s46
	s_mov_b32 s4, 0
	s_or_b32 s6, s6, 3
	v_or_b32_e32 v165, 32, v163
	v_or_b32_e32 v166, 33, v163
	v_or_b32_e32 v167, 2, v163
	v_or_b32_e32 v168, 34, v163
	v_or_b32_e32 v169, 3, v163
	v_or_b32_e32 v170, 35, v163
	v_or_b32_e32 v171, 8, v163
	v_or_b32_e32 v172, 40, v163
	v_or_b32_e32 v173, 9, v163
	v_or_b32_e32 v174, 41, v163
	v_or_b32_e32 v175, 10, v163
	v_or_b32_e32 v176, 42, v163
	v_or_b32_e32 v177, 11, v163
	v_or_b32_e32 v178, 43, v163
	v_or_b32_e32 v179, 16, v163
	v_or_b32_e32 v180, 48, v163
	v_or_b32_e32 v181, 17, v163
	v_or_b32_e32 v182, 49, v163
	v_or_b32_e32 v183, 18, v163
	v_or_b32_e32 v184, 50, v163
	v_or_b32_e32 v185, 19, v163
	v_or_b32_e32 v186, 51, v163
	v_or_b32_e32 v187, 24, v163
	v_or_b32_e32 v188, 56, v163
	v_or_b32_e32 v189, 25, v163
	v_or_b32_e32 v190, 57, v163
	v_or_b32_e32 v191, 26, v163
	v_or_b32_e32 v192, 58, v163
	v_or_b32_e32 v193, 27, v163
	v_or_b32_e32 v194, 59, v163
	s_addk_i32 s7, 0x400
	v_mov_b32_e32 v196, 0
	v_mov_b32_e32 v197, 0xf149f2ca
	s_mov_b32 s26, 63
	v_mov_b64_e32 v[14:15], v[12:13]
	v_mov_b64_e32 v[12:13], v[10:11]
	v_mov_b64_e32 v[10:11], v[8:9]
	v_mov_b64_e32 v[8:9], v[6:7]
	v_mov_b64_e32 v[6:7], v[4:5]
	v_mov_b64_e32 v[4:5], v[2:3]
	v_mov_b64_e32 v[2:3], v[0:1]
	s_waitcnt lgkmcnt(0)
	s_movk_i32 s68, 0x5000
	s_mov_b32 s69, 0
	s_mov_b32 s70, 0xe800
	s_mov_b32 s72, 0
	s_barrier
	v_readfirstlane_b32 s73, v255
	s_cmp_lt_u32 s73, 0x100
	s_cbranch_scc1 .Lyp649
	s_setprio 1

.LBB0_649:
	s_add_i32 s27, s0, -2
	s_and_b32 s27, s27, 1
	s_xor_b32 s34, s27, 1
	s_mul_i32 s35, s34, 0x4400
	s_add_i32 s35, s35, 0
	s_mulk_i32 s34, 0xc00
	s_add_i32 s34, s35, s34
	v_add3_u32 v0, s35, v157, v158
	s_waitcnt vmcnt(3)
	ds_write_b128 v0, v[130:133]
	v_add3_u32 v0, s68, v159, v158
	s_waitcnt vmcnt(2)
	ds_write_b128 v0, v[134:137] offset:34816
	v_add3_u32 v0, s35, v160, v161
	s_cmp_lt_u32 s0, s1
	s_waitcnt vmcnt(1)
	ds_write_b128 v0, v[138:141]
	v_add3_u32 v0, s68, v147, v161
	s_cselect_b32 s34, s0, s6
	s_lshl_b32 s34, s34, 20
	s_add_u32 s80, s78, s34
	s_addc_u32 s81, s79, 0
	s_add_u32 s80, s80, 0x1000
	s_addc_u32 s81, s81, 0
	s_add_u32 s82, s80, 0x1000
	s_addc_u32 s83, s81, 0
	s_waitcnt vmcnt(0)
	ds_write_b128 v0, v[142:145] offset:34816
	global_load_dwordx4 v[130:133], v150, s[80:81]
	global_load_dwordx4 v[134:137], v150, s[82:83]
	s_sub_i32 s34, s26, 63
	s_cmp_gt_i32 s34, s5
	global_load_dwordx4 v[138:141], v152, s[80:81]
	global_load_dwordx4 v[142:145], v152, s[82:83]
	s_sub_i32 s34, s26, 63
	s_cmp_gt_i32 s34, s5
	s_cbranch_scc1 .Lff1a_inact
	s_cmp_eq_u32 s72, 0
	s_cbranch_scc1 .Lff1a_first
	s_mul_i32 s34, s27, 0x4400
	v_add_u32_e32 v0, s34, v162
	ds_read_b128 v[198:201], v0
	ds_read_b128 v[202:205], v0 offset:32
	ds_read_b128 v[206:209], v0 offset:8704
	ds_read_b128 v[210:213], v0 offset:8736
	v_add_u32_e32 v246, s4, v149
	v_add_u32_e32 v234, 0x12800, v246
	v_add_u32_e32 v235, 0x12880, v246
	v_add_u32_e32 v238, 0x12820, v246
	v_add_u32_e32 v239, 0x128a0, v246
	v_add_u32_e32 v242, 0x12840, v246
	v_add_u32_e32 v243, 0x128c0, v246
	v_add_u32_e32 v247, 0x12860, v246
	v_add_u32_e32 v246, 0x128e0, v246
	ds_read_b128 v[218:221], v234
	ds_read_b128 v[234:237], v235
	ds_read_b128 v[222:225], v238
	ds_read_b128 v[238:241], v239
	ds_read_b128 v[226:229], v242
	ds_read_b128 v[242:245], v243
	ds_read_b128 v[230:233], v247
	ds_read_b128 v[246:249], v246
	s_waitcnt lgkmcnt(1)
	v_mfma_f32_32x32x16_bf16 v[218:233], v[198:201], v[98:101], v[218:233]
	v_sub_f32_e32 v82, v82, v197
	v_sub_f32_e32 v83, v83, v197
	v_sub_f32_e32 v84, v84, v197
	v_sub_f32_e32 v85, v85, v197
	v_exp_f32_e32 v82, v82
	v_exp_f32_e32 v83, v83
	v_exp_f32_e32 v84, v84
	v_exp_f32_e32 v85, v85
	s_waitcnt lgkmcnt(0)
	v_mfma_f32_32x32x16_bf16 v[234:249], v[206:209], v[98:101], v[234:249]
	v_sub_f32_e32 v86, v86, v197
	v_sub_f32_e32 v87, v87, v197
	v_sub_f32_e32 v88, v88, v197
	v_sub_f32_e32 v89, v89, v197
	v_exp_f32_e32 v86, v86
	v_exp_f32_e32 v87, v87
	v_exp_f32_e32 v88, v88
	v_exp_f32_e32 v89, v89
	v_mfma_f32_32x32x16_bf16 v[218:233], v[202:205], v[102:105], v[218:233]
	v_sub_f32_e32 v66, v66, v197
	v_sub_f32_e32 v67, v67, v197
	v_sub_f32_e32 v68, v68, v197
	v_sub_f32_e32 v69, v69, v197
	v_exp_f32_e32 v66, v66
	v_exp_f32_e32 v67, v67
	v_exp_f32_e32 v68, v68
	v_exp_f32_e32 v69, v69
	ds_read_b128 v[198:201], v0 offset:64
	ds_read_b128 v[202:205], v0 offset:96
	ds_read_b128 v[206:209], v0 offset:8768
	ds_read_b128 v[214:217], v0 offset:8800
	v_mfma_f32_32x32x16_bf16 v[234:249], v[210:213], v[102:105], v[234:249]
	v_add_f32_e32 v250, v82, v86
	v_add_f32_e32 v251, v83, v87
	v_add_f32_e32 v252, v84, v88
	v_add_f32_e32 v253, v85, v89
	v_sub_f32_e32 v70, v70, v197
	v_sub_f32_e32 v71, v71, v197
	v_sub_f32_e32 v72, v72, v197
	v_sub_f32_e32 v73, v73, v197
	s_waitcnt lgkmcnt(3)
	v_mfma_f32_32x32x16_bf16 v[218:233], v[198:201], v[106:109], v[218:233]
	v_exp_f32_e32 v70, v70
	v_exp_f32_e32 v71, v71
	v_exp_f32_e32 v72, v72
	v_exp_f32_e32 v73, v73
	v_add_f32_e32 v250, v250, v66
	v_add_f32_e32 v251, v251, v67
	v_add_f32_e32 v252, v252, v68
	v_add_f32_e32 v253, v253, v69
	s_waitcnt lgkmcnt(1)
	v_mfma_f32_32x32x16_bf16 v[234:249], v[206:209], v[106:109], v[234:249]
	v_sub_f32_e32 v90, v90, v197
	v_sub_f32_e32 v91, v91, v197
	v_sub_f32_e32 v92, v92, v197
	v_sub_f32_e32 v93, v93, v197
	v_exp_f32_e32 v90, v90
	v_exp_f32_e32 v91, v91
	v_exp_f32_e32 v92, v92
	v_exp_f32_e32 v93, v93
	v_mfma_f32_32x32x16_bf16 v[218:233], v[202:205], v[110:113], v[218:233]
	v_add_f32_e32 v250, v250, v70
	v_add_f32_e32 v251, v251, v71
	v_add_f32_e32 v252, v252, v72
	v_add_f32_e32 v253, v253, v73
	v_sub_f32_e32 v94, v94, v197
	v_sub_f32_e32 v95, v95, v197
	v_sub_f32_e32 v96, v96, v197
	v_sub_f32_e32 v97, v97, v197
	ds_read_b128 v[198:201], v0 offset:128
	ds_read_b128 v[202:205], v0 offset:160
	ds_read_b128 v[206:209], v0 offset:8832
	ds_read_b128 v[210:213], v0 offset:8864
	s_waitcnt lgkmcnt(4)
	v_mfma_f32_32x32x16_bf16 v[234:249], v[214:217], v[110:113], v[234:249]
	v_exp_f32_e32 v94, v94
	v_exp_f32_e32 v95, v95
	v_exp_f32_e32 v96, v96
	v_exp_f32_e32 v97, v97
	v_add_f32_e32 v250, v250, v90
	v_add_f32_e32 v251, v251, v91
	v_add_f32_e32 v252, v252, v92
	v_add_f32_e32 v253, v253, v93
	s_waitcnt lgkmcnt(3)
	v_mfma_f32_32x32x16_bf16 v[218:233], v[198:201], v[114:117], v[218:233]
	v_sub_f32_e32 v74, v74, v197
	v_sub_f32_e32 v75, v75, v197
	v_sub_f32_e32 v76, v76, v197
	v_sub_f32_e32 v77, v77, v197
	v_exp_f32_e32 v74, v74
	v_exp_f32_e32 v75, v75
	v_exp_f32_e32 v76, v76
	v_exp_f32_e32 v77, v77
	s_waitcnt lgkmcnt(1)
	v_mfma_f32_32x32x16_bf16 v[234:249], v[206:209], v[114:117], v[234:249]
	v_add_f32_e32 v250, v250, v94
	v_add_f32_e32 v251, v251, v95
	v_add_f32_e32 v252, v252, v96
	v_add_f32_e32 v253, v253, v97
	v_sub_f32_e32 v78, v78, v197
	v_sub_f32_e32 v79, v79, v197
	v_sub_f32_e32 v80, v80, v197
	v_sub_f32_e32 v81, v81, v197
	v_mfma_f32_32x32x16_bf16 v[218:233], v[202:205], v[118:121], v[218:233]
	v_exp_f32_e32 v78, v78
	v_exp_f32_e32 v79, v79
	v_exp_f32_e32 v80, v80
	v_exp_f32_e32 v81, v81
	v_add_f32_e32 v250, v250, v74
	v_add_f32_e32 v251, v251, v75
	v_add_f32_e32 v252, v252, v76
	v_add_f32_e32 v253, v253, v77
	ds_read_b128 v[198:201], v0 offset:192
	ds_read_b128 v[202:205], v0 offset:224
	ds_read_b128 v[206:209], v0 offset:8896
	ds_read_b128 v[214:217], v0 offset:8928
	s_waitcnt lgkmcnt(4)
	v_mfma_f32_32x32x16_bf16 v[234:249], v[210:213], v[118:121], v[234:249]
	v_add_f32_e32 v250, v250, v78
	v_add_f32_e32 v251, v251, v79
	v_add_f32_e32 v252, v252, v80
	v_add_f32_e32 v253, v253, v81
	v_add_f32_e32 v250, v250, v251
	v_add_f32_e32 v252, v252, v253
	v_add_f32_e32 v250, v250, v252
	v_add_f32_e32 v196, v196, v250
	s_waitcnt lgkmcnt(3)
	v_mfma_f32_32x32x16_bf16 v[218:233], v[198:201], v[122:125], v[218:233]
	v_cvt_pk_bf16_f32 v73, v72, v73
	v_cvt_pk_bf16_f32 v72, v70, v71
	v_cvt_pk_bf16_f32 v71, v68, v69
	v_cvt_pk_bf16_f32 v70, v66, v67
	v_cvt_pk_bf16_f32 v66, v82, v83
	v_cvt_pk_bf16_f32 v67, v84, v85
	v_cvt_pk_bf16_f32 v68, v86, v87
	v_cvt_pk_bf16_f32 v69, v88, v89
	s_waitcnt lgkmcnt(1)
	v_mfma_f32_32x32x16_bf16 v[234:249], v[206:209], v[122:125], v[234:249]
	v_cvt_pk_bf16_f32 v81, v80, v81
	v_cvt_pk_bf16_f32 v80, v78, v79
	v_cvt_pk_bf16_f32 v79, v76, v77
	v_cvt_pk_bf16_f32 v78, v74, v75
	v_cvt_pk_bf16_f32 v74, v90, v91
	v_cvt_pk_bf16_f32 v75, v92, v93
	v_cvt_pk_bf16_f32 v76, v94, v95
	v_cvt_pk_bf16_f32 v77, v96, v97
	v_mfma_f32_32x32x16_bf16 v[218:233], v[202:205], v[126:129], v[218:233]
	s_waitcnt lgkmcnt(0)
	v_mfma_f32_32x32x16_bf16 v[234:249], v[214:217], v[126:129], v[234:249]
	s_cmp_le_i32 s26, s5
	s_cbranch_scc1 .Lff1a_z2
	v_cmp_le_i32_e32 vcc, v165, v195
	s_nop 8
	v_cndmask_b32_e32 v234, v155, v234, vcc
	v_cmp_lt_i32_e32 vcc, v163, v195
	s_nop 1
	v_cndmask_b32_e32 v219, v155, v219, vcc
	v_cmp_le_i32_e32 vcc, v163, v195
	s_nop 1
	v_cndmask_b32_e32 v218, v155, v218, vcc
	v_cmp_le_i32_e32 vcc, v166, v195
	s_nop 1
	v_cndmask_b32_e32 v235, v155, v235, vcc
	v_cmp_le_i32_e32 vcc, v167, v195
	s_nop 1
	v_cndmask_b32_e32 v220, v155, v220, vcc
	v_cmp_le_i32_e32 vcc, v168, v195
	s_nop 1
	v_cndmask_b32_e32 v236, v155, v236, vcc
	v_cmp_le_i32_e32 vcc, v169, v195
	s_nop 1
	v_cndmask_b32_e32 v221, v155, v221, vcc
	v_cmp_le_i32_e32 vcc, v170, v195
	s_nop 1
	v_cndmask_b32_e32 v237, v155, v237, vcc
	v_cmp_le_i32_e32 vcc, v171, v195
	s_nop 1
	v_cndmask_b32_e32 v222, v155, v222, vcc
	v_cmp_le_i32_e32 vcc, v172, v195
	s_nop 1
	v_cndmask_b32_e32 v238, v155, v238, vcc
	v_cmp_le_i32_e32 vcc, v173, v195
	s_nop 1
	v_cndmask_b32_e32 v223, v155, v223, vcc
	v_cmp_le_i32_e32 vcc, v174, v195
	s_nop 1
	v_cndmask_b32_e32 v239, v155, v239, vcc
	v_cmp_le_i32_e32 vcc, v175, v195
	s_nop 1
	v_cndmask_b32_e32 v224, v155, v224, vcc
	v_cmp_le_i32_e32 vcc, v176, v195
	s_nop 1
	v_cndmask_b32_e32 v240, v155, v240, vcc
	v_cmp_le_i32_e32 vcc, v177, v195
	s_nop 1
	v_cndmask_b32_e32 v225, v155, v225, vcc
	v_cmp_le_i32_e32 vcc, v178, v195
	s_nop 1
	v_cndmask_b32_e32 v241, v155, v241, vcc
	v_cmp_le_i32_e32 vcc, v179, v195
	s_nop 1
	v_cndmask_b32_e32 v226, v155, v226, vcc
	v_cmp_le_i32_e32 vcc, v180, v195
	s_nop 1
	v_cndmask_b32_e32 v242, v155, v242, vcc
	v_cmp_le_i32_e32 vcc, v181, v195
	s_nop 1
	v_cndmask_b32_e32 v227, v155, v227, vcc
	v_cmp_le_i32_e32 vcc, v182, v195
	s_nop 1
	v_cndmask_b32_e32 v243, v155, v243, vcc
	v_cmp_le_i32_e32 vcc, v183, v195
	s_nop 1
	v_cndmask_b32_e32 v228, v155, v228, vcc
	v_cmp_le_i32_e32 vcc, v184, v195
	s_nop 1
	v_cndmask_b32_e32 v244, v155, v244, vcc
	v_cmp_le_i32_e32 vcc, v185, v195
	s_nop 1
	v_cndmask_b32_e32 v229, v155, v229, vcc
	v_cmp_le_i32_e32 vcc, v186, v195
	s_nop 1
	v_cndmask_b32_e32 v245, v155, v245, vcc
	v_cmp_le_i32_e32 vcc, v187, v195
	s_nop 1
	v_cndmask_b32_e32 v230, v155, v230, vcc
	v_cmp_le_i32_e32 vcc, v188, v195
	s_nop 1
	v_cndmask_b32_e32 v246, v155, v246, vcc
	v_cmp_le_i32_e32 vcc, v189, v195
	s_nop 1
	v_cndmask_b32_e32 v231, v155, v231, vcc
	v_cmp_le_i32_e32 vcc, v190, v195
	s_nop 1
	v_cndmask_b32_e32 v247, v155, v247, vcc
	v_cmp_le_i32_e32 vcc, v191, v195
	s_nop 1
	v_cndmask_b32_e32 v232, v155, v232, vcc
	v_cmp_le_i32_e32 vcc, v192, v195
	s_nop 1
	v_cndmask_b32_e32 v248, v155, v248, vcc
	v_cmp_le_i32_e32 vcc, v193, v195
	s_nop 1
	v_cndmask_b32_e32 v233, v155, v233, vcc
	v_cmp_le_i32_e32 vcc, v194, v195
	s_nop 1
	v_cndmask_b32_e32 v249, v155, v249, vcc

.Lff1b_top:
	s_add_i32 s27, s0, -2
	s_and_b32 s27, s27, 1
	s_xor_b32 s34, s27, 1
	s_mul_i32 s35, s34, 0x4400
	s_add_i32 s35, s35, 0
	s_mulk_i32 s34, 0xc00
	s_add_i32 s34, s35, s34
	v_add3_u32 v0, s35, v157, v158
	s_waitcnt vmcnt(3)
	ds_write_b128 v0, v[130:133]
	v_add3_u32 v0, s68, v159, v158
	s_waitcnt vmcnt(2)
	ds_write_b128 v0, v[134:137] offset:34816
	v_add3_u32 v0, s35, v160, v161
	s_cmp_lt_u32 s0, s1
	s_waitcnt vmcnt(1)
	ds_write_b128 v0, v[138:141]
	v_add3_u32 v0, s68, v147, v161
	s_cselect_b32 s34, s0, s6
	s_lshl_b32 s34, s34, 20
	s_add_u32 s80, s78, s34
	s_addc_u32 s81, s79, 0
	s_add_u32 s80, s80, 0x1000
	s_addc_u32 s81, s81, 0
	s_add_u32 s82, s80, 0x1000
	s_addc_u32 s83, s81, 0
	s_waitcnt vmcnt(0)
	ds_write_b128 v0, v[142:145] offset:34816
	global_load_dwordx4 v[130:133], v150, s[80:81]
	global_load_dwordx4 v[134:137], v150, s[82:83]
	s_sub_i32 s34, s26, 63
	s_cmp_gt_i32 s34, s5
	global_load_dwordx4 v[138:141], v152, s[80:81]
	global_load_dwordx4 v[142:145], v152, s[82:83]
	s_sub_i32 s34, s26, 63
	s_cmp_gt_i32 s34, s5
	s_cbranch_scc1 .Lff1b_inact
	s_cmp_eq_u32 s72, 0
	s_cbranch_scc1 .Lff1b_first
	s_mul_i32 s34, s27, 0x4400
	v_add_u32_e32 v0, s34, v162
	ds_read_b128 v[198:201], v0
	ds_read_b128 v[202:205], v0 offset:32
	ds_read_b128 v[206:209], v0 offset:8704
	ds_read_b128 v[210:213], v0 offset:8736
	v_add_u32_e32 v78, s4, v149
	v_add_u32_e32 v66, 0x12800, v78
	v_add_u32_e32 v67, 0x12880, v78
	v_add_u32_e32 v70, 0x12820, v78
	v_add_u32_e32 v71, 0x128a0, v78
	v_add_u32_e32 v74, 0x12840, v78
	v_add_u32_e32 v75, 0x128c0, v78
	v_add_u32_e32 v79, 0x12860, v78
	v_add_u32_e32 v78, 0x128e0, v78
	ds_read_b128 v[82:85], v66
	ds_read_b128 v[66:69], v67
	ds_read_b128 v[86:89], v70
	ds_read_b128 v[70:73], v71
	ds_read_b128 v[90:93], v74
	ds_read_b128 v[74:77], v75
	ds_read_b128 v[94:97], v79
	ds_read_b128 v[78:81], v78
	s_waitcnt lgkmcnt(1)
	v_mfma_f32_32x32x16_bf16 v[82:97], v[198:201], v[98:101], v[82:97]
	v_sub_f32_e32 v218, v218, v197
	v_sub_f32_e32 v219, v219, v197
	v_sub_f32_e32 v220, v220, v197
	v_sub_f32_e32 v221, v221, v197
	v_exp_f32_e32 v218, v218
	v_exp_f32_e32 v219, v219
	v_exp_f32_e32 v220, v220
	v_exp_f32_e32 v221, v221
	s_waitcnt lgkmcnt(0)
	v_mfma_f32_32x32x16_bf16 v[66:81], v[206:209], v[98:101], v[66:81]
	v_sub_f32_e32 v222, v222, v197
	v_sub_f32_e32 v223, v223, v197
	v_sub_f32_e32 v224, v224, v197
	v_sub_f32_e32 v225, v225, v197
	v_exp_f32_e32 v222, v222
	v_exp_f32_e32 v223, v223
	v_exp_f32_e32 v224, v224
	v_exp_f32_e32 v225, v225
	v_mfma_f32_32x32x16_bf16 v[82:97], v[202:205], v[102:105], v[82:97]
	v_sub_f32_e32 v234, v234, v197
	v_sub_f32_e32 v235, v235, v197
	v_sub_f32_e32 v236, v236, v197
	v_sub_f32_e32 v237, v237, v197
	v_exp_f32_e32 v234, v234
	v_exp_f32_e32 v235, v235
	v_exp_f32_e32 v236, v236
	v_exp_f32_e32 v237, v237
	ds_read_b128 v[198:201], v0 offset:64
	ds_read_b128 v[202:205], v0 offset:96
	ds_read_b128 v[206:209], v0 offset:8768
	ds_read_b128 v[214:217], v0 offset:8800
	v_mfma_f32_32x32x16_bf16 v[66:81], v[210:213], v[102:105], v[66:81]
	v_add_f32_e32 v250, v218, v222
	v_add_f32_e32 v251, v219, v223
	v_add_f32_e32 v252, v220, v224
	v_add_f32_e32 v253, v221, v225
	v_sub_f32_e32 v238, v238, v197
	v_sub_f32_e32 v239, v239, v197
	v_sub_f32_e32 v240, v240, v197
	v_sub_f32_e32 v241, v241, v197
	s_waitcnt lgkmcnt(3)
	v_mfma_f32_32x32x16_bf16 v[82:97], v[198:201], v[106:109], v[82:97]
	v_exp_f32_e32 v238, v238
	v_exp_f32_e32 v239, v239
	v_exp_f32_e32 v240, v240
	v_exp_f32_e32 v241, v241
	v_add_f32_e32 v250, v250, v234
	v_add_f32_e32 v251, v251, v235
	v_add_f32_e32 v252, v252, v236
	v_add_f32_e32 v253, v253, v237
	s_waitcnt lgkmcnt(1)
	v_mfma_f32_32x32x16_bf16 v[66:81], v[206:209], v[106:109], v[66:81]
	v_sub_f32_e32 v226, v226, v197
	v_sub_f32_e32 v227, v227, v197
	v_sub_f32_e32 v228, v228, v197
	v_sub_f32_e32 v229, v229, v197
	v_exp_f32_e32 v226, v226
	v_exp_f32_e32 v227, v227
	v_exp_f32_e32 v228, v228
	v_exp_f32_e32 v229, v229
	v_mfma_f32_32x32x16_bf16 v[82:97], v[202:205], v[110:113], v[82:97]
	v_add_f32_e32 v250, v250, v238
	v_add_f32_e32 v251, v251, v239
	v_add_f32_e32 v252, v252, v240
	v_add_f32_e32 v253, v253, v241
	v_sub_f32_e32 v230, v230, v197
	v_sub_f32_e32 v231, v231, v197
	v_sub_f32_e32 v232, v232, v197
	v_sub_f32_e32 v233, v233, v197
	ds_read_b128 v[198:201], v0 offset:128
	ds_read_b128 v[202:205], v0 offset:160
	ds_read_b128 v[206:209], v0 offset:8832
	ds_read_b128 v[210:213], v0 offset:8864
	s_waitcnt lgkmcnt(4)
	v_mfma_f32_32x32x16_bf16 v[66:81], v[214:217], v[110:113], v[66:81]
	v_exp_f32_e32 v230, v230
	v_exp_f32_e32 v231, v231
	v_exp_f32_e32 v232, v232
	v_exp_f32_e32 v233, v233
	v_add_f32_e32 v250, v250, v226
	v_add_f32_e32 v251, v251, v227
	v_add_f32_e32 v252, v252, v228
	v_add_f32_e32 v253, v253, v229
	s_waitcnt lgkmcnt(3)
	v_mfma_f32_32x32x16_bf16 v[82:97], v[198:201], v[114:117], v[82:97]
	v_sub_f32_e32 v242, v242, v197
	v_sub_f32_e32 v243, v243, v197
	v_sub_f32_e32 v244, v244, v197
	v_sub_f32_e32 v245, v245, v197
	v_exp_f32_e32 v242, v242
	v_exp_f32_e32 v243, v243
	v_exp_f32_e32 v244, v244
	v_exp_f32_e32 v245, v245
	s_waitcnt lgkmcnt(1)
	v_mfma_f32_32x32x16_bf16 v[66:81], v[206:209], v[114:117], v[66:81]
	v_add_f32_e32 v250, v250, v230
	v_add_f32_e32 v251, v251, v231
	v_add_f32_e32 v252, v252, v232
	v_add_f32_e32 v253, v253, v233
	v_sub_f32_e32 v246, v246, v197
	v_sub_f32_e32 v247, v247, v197
	v_sub_f32_e32 v248, v248, v197
	v_sub_f32_e32 v249, v249, v197
	v_mfma_f32_32x32x16_bf16 v[82:97], v[202:205], v[118:121], v[82:97]
	v_exp_f32_e32 v246, v246
	v_exp_f32_e32 v247, v247
	v_exp_f32_e32 v248, v248
	v_exp_f32_e32 v249, v249
	v_add_f32_e32 v250, v250, v242
	v_add_f32_e32 v251, v251, v243
	v_add_f32_e32 v252, v252, v244
	v_add_f32_e32 v253, v253, v245
	ds_read_b128 v[198:201], v0 offset:192
	ds_read_b128 v[202:205], v0 offset:224
	ds_read_b128 v[206:209], v0 offset:8896
	ds_read_b128 v[214:217], v0 offset:8928
	s_waitcnt lgkmcnt(4)
	v_mfma_f32_32x32x16_bf16 v[66:81], v[210:213], v[118:121], v[66:81]
	v_add_f32_e32 v250, v250, v246
	v_add_f32_e32 v251, v251, v247
	v_add_f32_e32 v252, v252, v248
	v_add_f32_e32 v253, v253, v249
	v_add_f32_e32 v250, v250, v251
	v_add_f32_e32 v252, v252, v253
	v_add_f32_e32 v250, v250, v252
	v_add_f32_e32 v196, v196, v250
	s_waitcnt lgkmcnt(3)
	v_mfma_f32_32x32x16_bf16 v[82:97], v[198:201], v[122:125], v[82:97]
	v_cvt_pk_bf16_f32 v241, v240, v241
	v_cvt_pk_bf16_f32 v240, v238, v239
	v_cvt_pk_bf16_f32 v239, v236, v237
	v_cvt_pk_bf16_f32 v238, v234, v235
	v_cvt_pk_bf16_f32 v234, v218, v219
	v_cvt_pk_bf16_f32 v235, v220, v221
	v_cvt_pk_bf16_f32 v236, v222, v223
	v_cvt_pk_bf16_f32 v237, v224, v225
	s_waitcnt lgkmcnt(1)
	v_mfma_f32_32x32x16_bf16 v[66:81], v[206:209], v[122:125], v[66:81]
	v_cvt_pk_bf16_f32 v249, v248, v249
	v_cvt_pk_bf16_f32 v248, v246, v247
	v_cvt_pk_bf16_f32 v247, v244, v245
	v_cvt_pk_bf16_f32 v246, v242, v243
	v_cvt_pk_bf16_f32 v242, v226, v227
	v_cvt_pk_bf16_f32 v243, v228, v229
	v_cvt_pk_bf16_f32 v244, v230, v231
	v_cvt_pk_bf16_f32 v245, v232, v233
	v_mfma_f32_32x32x16_bf16 v[82:97], v[202:205], v[126:129], v[82:97]
	s_waitcnt lgkmcnt(0)
	v_mfma_f32_32x32x16_bf16 v[66:81], v[214:217], v[126:129], v[66:81]
	s_cmp_le_i32 s26, s5
	s_cbranch_scc1 .Lff1b_z2
	v_cmp_le_i32_e32 vcc, v165, v195
	s_nop 8
	v_cndmask_b32_e32 v66, v155, v66, vcc
	v_cmp_lt_i32_e32 vcc, v163, v195
	s_nop 1
	v_cndmask_b32_e32 v83, v155, v83, vcc
	v_cmp_le_i32_e32 vcc, v163, v195
	s_nop 1
	v_cndmask_b32_e32 v82, v155, v82, vcc
	v_cmp_le_i32_e32 vcc, v166, v195
	s_nop 1
	v_cndmask_b32_e32 v67, v155, v67, vcc
	v_cmp_le_i32_e32 vcc, v167, v195
	s_nop 1
	v_cndmask_b32_e32 v84, v155, v84, vcc
	v_cmp_le_i32_e32 vcc, v168, v195
	s_nop 1
	v_cndmask_b32_e32 v68, v155, v68, vcc
	v_cmp_le_i32_e32 vcc, v169, v195
	s_nop 1
	v_cndmask_b32_e32 v85, v155, v85, vcc
	v_cmp_le_i32_e32 vcc, v170, v195
	s_nop 1
	v_cndmask_b32_e32 v69, v155, v69, vcc
	v_cmp_le_i32_e32 vcc, v171, v195
	s_nop 1
	v_cndmask_b32_e32 v86, v155, v86, vcc
	v_cmp_le_i32_e32 vcc, v172, v195
	s_nop 1
	v_cndmask_b32_e32 v70, v155, v70, vcc
	v_cmp_le_i32_e32 vcc, v173, v195
	s_nop 1
	v_cndmask_b32_e32 v87, v155, v87, vcc
	v_cmp_le_i32_e32 vcc, v174, v195
	s_nop 1
	v_cndmask_b32_e32 v71, v155, v71, vcc
	v_cmp_le_i32_e32 vcc, v175, v195
	s_nop 1
	v_cndmask_b32_e32 v88, v155, v88, vcc
	v_cmp_le_i32_e32 vcc, v176, v195
	s_nop 1
	v_cndmask_b32_e32 v72, v155, v72, vcc
	v_cmp_le_i32_e32 vcc, v177, v195
	s_nop 1
	v_cndmask_b32_e32 v89, v155, v89, vcc
	v_cmp_le_i32_e32 vcc, v178, v195
	s_nop 1
	v_cndmask_b32_e32 v73, v155, v73, vcc
	v_cmp_le_i32_e32 vcc, v179, v195
	s_nop 1
	v_cndmask_b32_e32 v90, v155, v90, vcc
	v_cmp_le_i32_e32 vcc, v180, v195
	s_nop 1
	v_cndmask_b32_e32 v74, v155, v74, vcc
	v_cmp_le_i32_e32 vcc, v181, v195
	s_nop 1
	v_cndmask_b32_e32 v91, v155, v91, vcc
	v_cmp_le_i32_e32 vcc, v182, v195
	s_nop 1
	v_cndmask_b32_e32 v75, v155, v75, vcc
	v_cmp_le_i32_e32 vcc, v183, v195
	s_nop 1
	v_cndmask_b32_e32 v92, v155, v92, vcc
	v_cmp_le_i32_e32 vcc, v184, v195
	s_nop 1
	v_cndmask_b32_e32 v76, v155, v76, vcc
	v_cmp_le_i32_e32 vcc, v185, v195
	s_nop 1
	v_cndmask_b32_e32 v93, v155, v93, vcc
	v_cmp_le_i32_e32 vcc, v186, v195
	s_nop 1
	v_cndmask_b32_e32 v77, v155, v77, vcc
	v_cmp_le_i32_e32 vcc, v187, v195
	s_nop 1
	v_cndmask_b32_e32 v94, v155, v94, vcc
	v_cmp_le_i32_e32 vcc, v188, v195
	s_nop 1
	v_cndmask_b32_e32 v78, v155, v78, vcc
	v_cmp_le_i32_e32 vcc, v189, v195
	s_nop 1
	v_cndmask_b32_e32 v95, v155, v95, vcc
	v_cmp_le_i32_e32 vcc, v190, v195
	s_nop 1
	v_cndmask_b32_e32 v79, v155, v79, vcc
	v_cmp_le_i32_e32 vcc, v191, v195
	s_nop 1
	v_cndmask_b32_e32 v96, v155, v96, vcc
	v_cmp_le_i32_e32 vcc, v192, v195
	s_nop 1
	v_cndmask_b32_e32 v80, v155, v80, vcc
	v_cmp_le_i32_e32 vcc, v193, v195
	s_nop 1
	v_cndmask_b32_e32 v97, v155, v97, vcc
	v_cmp_le_i32_e32 vcc, v194, v195
	s_nop 1
	v_cndmask_b32_e32 v81, v155, v81, vcc

.LBB0_654:
	s_setprio 0
	v_mov_b32_e32 v0, v196
	v_nop
	v_nop
	v_permlane32_swap_b32 v196, v0
	s_lshl_b32 s16, s16, 1
	v_add_f32_e32 v146, v196, v0
	v_ashrrev_i32_e32 v0, 31, v156
	v_lshrrev_b32_e32 v0, 28, v0
	v_add_u32_e32 v0, v156, v0
	s_waitcnt vmcnt(0)
	v_ashrrev_i32_e32 v144, 4, v0
	v_and_b32_e32 v0, -16, v0
	v_sub_u32_e32 v147, v156, v0
	v_lshlrev_b32_e32 v68, 3, v147
	v_ashrrev_i32_e32 v69, 31, v68
	v_add_u32_e32 v0, 64, v156
	v_lshlrev_b64 v[140:141], 1, v[68:69]
	v_ashrrev_i32_e32 v68, 31, v0
	v_lshrrev_b32_e32 v68, 28, v68
	v_ashrrev_i32_e32 v145, 31, v144
	v_add_u32_e32 v68, v0, v68
	v_lshl_add_u64 v[138:139], s[24:25], 0, v[144:145]
	v_ashrrev_i32_e32 v142, 4, v68
	v_lshlrev_b64 v[66:67], 14, v[138:139]
	v_and_b32_e32 v68, -16, v68
	v_ashrrev_i32_e32 v143, 31, v142
	v_lshl_add_u64 v[66:67], s[12:13], 0, v[66:67]
	v_sub_u32_e32 v145, v0, v68
	v_lshl_add_u64 v[132:133], s[24:25], 0, v[142:143]
	v_lshl_add_u64 v[66:67], v[66:67], 0, s[16:17]
	v_lshlrev_b64 v[68:69], 14, v[132:133]
	v_lshlrev_b32_e32 v70, 3, v145
	v_lshl_add_u64 v[66:67], v[66:67], 0, v[140:141]
	v_lshl_add_u64 v[68:69], s[12:13], 0, v[68:69]
	v_ashrrev_i32_e32 v71, 31, v70
	v_add_co_u32_e32 v66, vcc, s48, v66
	v_lshl_add_u64 v[68:69], v[68:69], 0, s[16:17]
	v_lshlrev_b64 v[134:135], 1, v[70:71]
	v_addc_co_u32_e32 v67, vcc, 0, v67, vcc
	v_lshl_add_u64 v[68:69], v[68:69], 0, v[134:135]
	v_add_co_u32_e32 v68, vcc, s48, v68
	v_add_u32_e32 v0, 0x80, v156
	s_nop 0
	v_addc_co_u32_e32 v69, vcc, 0, v69, vcc
	global_load_dwordx4 v[94:97], v[66:67], off
	global_load_dwordx4 v[90:93], v[68:69], off
	v_ashrrev_i32_e32 v66, 31, v0
	v_lshrrev_b32_e32 v66, 28, v66
	v_add_u32_e32 v66, v0, v66
	v_ashrrev_i32_e32 v136, 4, v66
	v_and_b32_e32 v66, -16, v66
	v_sub_u32_e32 v143, v0, v66
	v_lshlrev_b32_e32 v68, 3, v143
	v_ashrrev_i32_e32 v69, 31, v68
	v_add_u32_e32 v0, 0xc0, v156
	v_lshlrev_b64 v[128:129], 1, v[68:69]
	v_ashrrev_i32_e32 v68, 31, v0
	v_lshrrev_b32_e32 v68, 28, v68
	v_ashrrev_i32_e32 v137, 31, v136
	v_add_u32_e32 v68, v0, v68
	v_lshl_add_u64 v[126:127], s[24:25], 0, v[136:137]
	v_ashrrev_i32_e32 v130, 4, v68
	v_lshlrev_b64 v[66:67], 14, v[126:127]
	v_and_b32_e32 v68, -16, v68
	v_ashrrev_i32_e32 v131, 31, v130
	v_lshl_add_u64 v[66:67], s[12:13], 0, v[66:67]
	v_sub_u32_e32 v137, v0, v68
	v_lshl_add_u64 v[120:121], s[24:25], 0, v[130:131]
	v_lshl_add_u64 v[66:67], v[66:67], 0, s[16:17]
	v_lshlrev_b64 v[68:69], 14, v[120:121]
	v_lshlrev_b32_e32 v70, 3, v137
	v_lshl_add_u64 v[66:67], v[66:67], 0, v[128:129]
	v_lshl_add_u64 v[68:69], s[12:13], 0, v[68:69]
	v_ashrrev_i32_e32 v71, 31, v70
	v_add_co_u32_e32 v66, vcc, s48, v66
	v_lshl_add_u64 v[68:69], v[68:69], 0, s[16:17]
	v_lshlrev_b64 v[122:123], 1, v[70:71]
	v_addc_co_u32_e32 v67, vcc, 0, v67, vcc
	v_lshl_add_u64 v[68:69], v[68:69], 0, v[122:123]
	v_add_co_u32_e32 v68, vcc, s48, v68
	v_add_u32_e32 v0, 0x100, v156
	s_nop 0
	v_addc_co_u32_e32 v69, vcc, 0, v69, vcc
	global_load_dwordx4 v[86:89], v[66:67], off
	global_load_dwordx4 v[82:85], v[68:69], off
	v_ashrrev_i32_e32 v66, 31, v0
	v_lshrrev_b32_e32 v66, 28, v66
	v_add_u32_e32 v66, v0, v66
	v_ashrrev_i32_e32 v124, 4, v66
	v_and_b32_e32 v66, -16, v66
	v_sub_u32_e32 v131, v0, v66
	v_lshlrev_b32_e32 v68, 3, v131
	v_ashrrev_i32_e32 v69, 31, v68
	v_add_u32_e32 v0, 0x140, v156
	v_lshlrev_b64 v[116:117], 1, v[68:69]
	v_ashrrev_i32_e32 v68, 31, v0
	v_lshrrev_b32_e32 v68, 28, v68
	v_ashrrev_i32_e32 v125, 31, v124
	v_add_u32_e32 v68, v0, v68
	v_lshl_add_u64 v[114:115], s[24:25], 0, v[124:125]
	v_ashrrev_i32_e32 v118, 4, v68
	v_lshlrev_b64 v[66:67], 14, v[114:115]
	v_and_b32_e32 v68, -16, v68
	v_ashrrev_i32_e32 v119, 31, v118
	v_lshl_add_u64 v[66:67], s[12:13], 0, v[66:67]
	v_sub_u32_e32 v125, v0, v68
	v_lshl_add_u64 v[108:109], s[24:25], 0, v[118:119]
	v_lshl_add_u64 v[66:67], v[66:67], 0, s[16:17]
	v_lshlrev_b64 v[68:69], 14, v[108:109]
	v_lshlrev_b32_e32 v70, 3, v125
	v_lshl_add_u64 v[66:67], v[66:67], 0, v[116:117]
	v_lshl_add_u64 v[68:69], s[12:13], 0, v[68:69]
	v_ashrrev_i32_e32 v71, 31, v70
	v_add_co_u32_e32 v66, vcc, s48, v66
	v_lshl_add_u64 v[68:69], v[68:69], 0, s[16:17]
	v_lshlrev_b64 v[110:111], 1, v[70:71]
	v_addc_co_u32_e32 v67, vcc, 0, v67, vcc
	v_lshl_add_u64 v[68:69], v[68:69], 0, v[110:111]
	v_add_co_u32_e32 v68, vcc, s48, v68
	v_add_u32_e32 v0, 0x180, v156
	s_nop 0
	v_addc_co_u32_e32 v69, vcc, 0, v69, vcc
	global_load_dwordx4 v[78:81], v[66:67], off
	global_load_dwordx4 v[74:77], v[68:69], off
	v_ashrrev_i32_e32 v66, 31, v0
	v_lshrrev_b32_e32 v66, 28, v66
	v_add_u32_e32 v66, v0, v66
	v_ashrrev_i32_e32 v112, 4, v66
	v_and_b32_e32 v66, -16, v66
	v_sub_u32_e32 v119, v0, v66
	v_lshlrev_b32_e32 v68, 3, v119
	v_ashrrev_i32_e32 v69, 31, v68
	v_add_u32_e32 v0, 0x1c0, v156
	v_lshlrev_b64 v[104:105], 1, v[68:69]
	v_ashrrev_i32_e32 v68, 31, v0
	v_lshrrev_b32_e32 v68, 28, v68
	v_ashrrev_i32_e32 v113, 31, v112
	v_add_u32_e32 v68, v0, v68
	v_lshl_add_u64 v[102:103], s[24:25], 0, v[112:113]
	v_ashrrev_i32_e32 v106, 4, v68
	v_lshlrev_b64 v[66:67], 14, v[102:103]
	v_and_b32_e32 v68, -16, v68
	v_ashrrev_i32_e32 v107, 31, v106
	s_and_b32 s0, s49, 7
	v_lshl_add_u64 v[66:67], s[12:13], 0, v[66:67]
	v_sub_u32_e32 v0, v0, v68
	v_lshl_add_u64 v[98:99], s[24:25], 0, v[106:107]
	s_lshl_b32 s7, s0, 8
	s_lshl_b32 s6, s0, 10
	v_lshl_add_u64 v[66:67], v[66:67], 0, s[16:17]
	v_lshlrev_b64 v[68:69], 14, v[98:99]
	v_lshlrev_b32_e32 v70, 3, v0
	v_div_scale_f32 v107, s[0:1], v146, v146, 1.0
	v_lshl_add_u64 v[66:67], v[66:67], 0, v[104:105]
	v_lshl_add_u64 v[68:69], s[12:13], 0, v[68:69]
	v_ashrrev_i32_e32 v71, 31, v70
	v_rcp_f32_e32 v113, v107
	v_add_co_u32_e32 v66, vcc, s48, v66
	v_lshl_add_u64 v[68:69], v[68:69], 0, s[16:17]
	v_lshlrev_b64 v[100:101], 1, v[70:71]
	v_addc_co_u32_e32 v67, vcc, 0, v67, vcc
	v_lshl_add_u64 v[68:69], v[68:69], 0, v[100:101]
	v_add_co_u32_e32 v68, vcc, s48, v68
	v_fma_f32 v148, -v107, v113, 1.0
	s_nop 0
	v_addc_co_u32_e32 v69, vcc, 0, v69, vcc
	v_fmac_f32_e32 v113, v148, v113
	v_div_scale_f32 v148, vcc, 1.0, v146, 1.0
	v_mul_f32_e32 v149, v148, v113
	v_fma_f32 v150, -v107, v149, v148
	v_fmac_f32_e32 v149, v150, v113
	v_fma_f32 v107, -v107, v149, v148
	v_div_fmas_f32 v107, v107, v113, v149
	v_div_fixup_f32 v146, v107, v146, 1.0
	v_pk_mul_f32 v[50:51], v[50:51], v[146:147] op_sel_hi:[1,0]
	v_pk_mul_f32 v[52:53], v[52:53], v[146:147] op_sel_hi:[1,0]
	s_mulk_i32 s33, 0x110
	v_and_b32_e32 v107, 31, v156
	v_cvt_pk_bf16_f32 v50, v50, v51
	v_cvt_pk_bf16_f32 v51, v52, v53
	v_ashrrev_i32_e32 v52, 2, v156
	v_pk_mul_f32 v[2:3], v[2:3], v[146:147] op_sel_hi:[1,0]
	v_pk_mul_f32 v[4:5], v[4:5], v[146:147] op_sel_hi:[1,0]
	s_add_i32 s4, s33, 0
	v_mul_u32_u24_e32 v107, 0x110, v107
	v_and_b32_e32 v52, -8, v52
	v_cvt_pk_bf16_f32 v2, v2, v3
	v_cvt_pk_bf16_f32 v3, v4, v5
	v_pk_mul_f32 v[4:5], v[6:7], v[146:147] op_sel_hi:[1,0]
	v_pk_mul_f32 v[6:7], v[8:9], v[146:147] op_sel_hi:[1,0]
	v_add3_u32 v107, s4, v107, v52
	v_cvt_pk_bf16_f32 v4, v4, v5
	v_cvt_pk_bf16_f32 v5, v6, v7
	global_load_dwordx4 v[70:73], v[66:67], off
	s_nop 0
	global_load_dwordx4 v[66:69], v[68:69], off
	v_pk_mul_f32 v[34:35], v[34:35], v[146:147] op_sel_hi:[1,0]
	v_pk_mul_f32 v[36:37], v[36:37], v[146:147] op_sel_hi:[1,0]
	v_pk_mul_f32 v[18:19], v[18:19], v[146:147] op_sel_hi:[1,0]
	v_pk_mul_f32 v[20:21], v[20:21], v[146:147] op_sel_hi:[1,0]
	ds_write2_b64 v107, v[2:3], v[4:5] offset0:24 offset1:26
	v_pk_mul_f32 v[2:3], v[10:11], v[146:147] op_sel_hi:[1,0]
	v_pk_mul_f32 v[4:5], v[12:13], v[146:147] op_sel_hi:[1,0]
	v_pk_mul_f32 v[52:53], v[54:55], v[146:147] op_sel_hi:[1,0]
	v_pk_mul_f32 v[54:55], v[56:57], v[146:147] op_sel_hi:[1,0]
	v_cvt_pk_bf16_f32 v34, v34, v35
	v_cvt_pk_bf16_f32 v35, v36, v37
	v_pk_mul_f32 v[36:37], v[38:39], v[146:147] op_sel_hi:[1,0]
	v_pk_mul_f32 v[38:39], v[40:41], v[146:147] op_sel_hi:[1,0]
	v_cvt_pk_bf16_f32 v18, v18, v19
	v_cvt_pk_bf16_f32 v19, v20, v21
	v_pk_mul_f32 v[20:21], v[22:23], v[146:147] op_sel_hi:[1,0]
	v_pk_mul_f32 v[22:23], v[24:25], v[146:147] op_sel_hi:[1,0]
	v_cvt_pk_bf16_f32 v2, v2, v3
	v_cvt_pk_bf16_f32 v3, v4, v5
	v_pk_mul_f32 v[4:5], v[14:15], v[146:147] op_sel_hi:[1,0]
	v_pk_mul_f32 v[6:7], v[16:17], v[146:147] op_sel_hi:[1,0]
	v_cvt_pk_bf16_f32 v52, v52, v53
	v_cvt_pk_bf16_f32 v53, v54, v55
	v_cvt_pk_bf16_f32 v36, v36, v37
	v_cvt_pk_bf16_f32 v37, v38, v39
	v_cvt_pk_bf16_f32 v20, v20, v21
	v_cvt_pk_bf16_f32 v21, v22, v23
	v_cvt_pk_bf16_f32 v4, v4, v5
	v_cvt_pk_bf16_f32 v5, v6, v7
	ds_write2_b64 v107, v[50:51], v[52:53] offset1:2
	v_pk_mul_f32 v[50:51], v[58:59], v[146:147] op_sel_hi:[1,0]
	v_pk_mul_f32 v[52:53], v[60:61], v[146:147] op_sel_hi:[1,0]
	ds_write2_b64 v107, v[34:35], v[36:37] offset0:8 offset1:10
	v_pk_mul_f32 v[34:35], v[42:43], v[146:147] op_sel_hi:[1,0]
	v_pk_mul_f32 v[36:37], v[44:45], v[146:147] op_sel_hi:[1,0]
	ds_write2_b64 v107, v[18:19], v[20:21] offset0:16 offset1:18
	v_pk_mul_f32 v[18:19], v[26:27], v[146:147] op_sel_hi:[1,0]
	v_pk_mul_f32 v[20:21], v[28:29], v[146:147] op_sel_hi:[1,0]
	ds_write2_b64 v107, v[2:3], v[4:5] offset0:28 offset1:30
	v_mul_lo_u32 v2, v144, s45
	v_lshlrev_b32_e32 v3, 4, v147
	s_waitcnt vmcnt(7)
	v_lshlrev_b32_e32 v10, 16, v94
	v_cvt_pk_bf16_f32 v50, v50, v51
	v_cvt_pk_bf16_f32 v51, v52, v53
	v_pk_mul_f32 v[52:53], v[62:63], v[146:147] op_sel_hi:[1,0]
	v_pk_mul_f32 v[54:55], v[64:65], v[146:147] op_sel_hi:[1,0]
	v_cvt_pk_bf16_f32 v34, v34, v35
	v_cvt_pk_bf16_f32 v35, v36, v37
	v_pk_mul_f32 v[36:37], v[46:47], v[146:147] op_sel_hi:[1,0]
	v_pk_mul_f32 v[38:39], v[48:49], v[146:147] op_sel_hi:[1,0]
	v_cvt_pk_bf16_f32 v18, v18, v19
	v_cvt_pk_bf16_f32 v19, v20, v21
	v_pk_mul_f32 v[20:21], v[30:31], v[146:147] op_sel_hi:[1,0]
	v_pk_mul_f32 v[22:23], v[32:33], v[146:147] op_sel_hi:[1,0]
	v_add3_u32 v2, s4, v2, v3
	v_and_b32_e32 v13, 0xffff0000, v94
	v_mul_f32_e32 v3, 0xbfb8aa3b, v10
	v_cvt_pk_bf16_f32 v52, v52, v53
	v_cvt_pk_bf16_f32 v53, v54, v55
	v_cvt_pk_bf16_f32 v36, v36, v37
	v_cvt_pk_bf16_f32 v37, v38, v39
	v_cvt_pk_bf16_f32 v20, v20, v21
	v_cvt_pk_bf16_f32 v21, v22, v23
	v_exp_f32_e32 v6, v3
	v_mul_f32_e32 v3, 0xbfb8aa3b, v13
	ds_write2_b64 v107, v[50:51], v[52:53] offset0:4 offset1:6
	ds_write2_b64 v107, v[34:35], v[36:37] offset0:12 offset1:14
	ds_write2_b64 v107, v[18:19], v[20:21] offset0:20 offset1:22
	v_exp_f32_e32 v7, v3
	s_waitcnt lgkmcnt(0)
	ds_read_b128 v[2:5], v2
	v_add_f32_e32 v6, 1.0, v6
	v_rcp_f32_e32 v14, v6
	v_add_f32_e32 v6, 1.0, v7
	v_rcp_f32_e32 v15, v6
	v_mul_lo_u32 v6, v142, s45
	v_lshlrev_b32_e32 v7, 4, v145
	v_add3_u32 v6, s4, v6, v7
	ds_read_b128 v[6:9], v6
	s_waitcnt lgkmcnt(1)
	v_and_b32_e32 v11, 0xffff0000, v2
	v_lshlrev_b32_e32 v12, 16, v2
	v_pk_mul_f32 v[10:11], v[12:13], v[10:11]
	v_lshlrev_b32_e32 v12, 16, v95
	v_pk_mul_f32 v[10:11], v[14:15], v[10:11]
	v_and_b32_e32 v15, 0xffff0000, v95
	v_mul_f32_e32 v2, 0xbfb8aa3b, v12
	v_exp_f32_e32 v13, v2
	v_mul_f32_e32 v2, 0xbfb8aa3b, v15
	v_exp_f32_e32 v14, v2
	v_cvt_pk_bf16_f32 v2, v10, v11
	v_add_f32_e32 v10, 1.0, v13
	v_rcp_f32_e32 v10, v10
	v_add_f32_e32 v11, 1.0, v14
	v_rcp_f32_e32 v11, v11
	v_and_b32_e32 v13, 0xffff0000, v3
	v_lshlrev_b32_e32 v14, 16, v3
	v_pk_mul_f32 v[12:13], v[14:15], v[12:13]
	v_and_b32_e32 v15, 0xffff0000, v96
	v_pk_mul_f32 v[10:11], v[10:11], v[12:13]
	v_lshlrev_b32_e32 v12, 16, v96
	v_mul_f32_e32 v3, 0xbfb8aa3b, v12
	v_exp_f32_e32 v13, v3
	v_mul_f32_e32 v3, 0xbfb8aa3b, v15
	v_exp_f32_e32 v14, v3
	v_cvt_pk_bf16_f32 v3, v10, v11
	v_add_f32_e32 v10, 1.0, v13
	v_rcp_f32_e32 v10, v10
	v_add_f32_e32 v11, 1.0, v14
	v_rcp_f32_e32 v11, v11
	v_and_b32_e32 v13, 0xffff0000, v4
	v_lshlrev_b32_e32 v14, 16, v4
	v_pk_mul_f32 v[12:13], v[14:15], v[12:13]
	v_and_b32_e32 v15, 0xffff0000, v97
	v_pk_mul_f32 v[10:11], v[10:11], v[12:13]
	v_lshlrev_b32_e32 v12, 16, v97
	v_mul_f32_e32 v4, 0xbfb8aa3b, v12
	v_exp_f32_e32 v13, v4
	v_mul_f32_e32 v4, 0xbfb8aa3b, v15
	v_exp_f32_e32 v14, v4
	v_cvt_pk_bf16_f32 v4, v10, v11
	v_add_f32_e32 v10, 1.0, v13
	v_rcp_f32_e32 v10, v10
	v_add_f32_e32 v11, 1.0, v14
	v_rcp_f32_e32 v11, v11
	v_and_b32_e32 v13, 0xffff0000, v5
	v_lshlrev_b32_e32 v14, 16, v5
	v_pk_mul_f32 v[12:13], v[14:15], v[12:13]
	s_waitcnt vmcnt(6)
	v_and_b32_e32 v15, 0xffff0000, v90
	v_pk_mul_f32 v[10:11], v[10:11], v[12:13]
	v_lshlrev_b32_e32 v12, 16, v90
	s_addk_i32 s6, 0x400
	v_mul_f32_e32 v13, 0xbfb8aa3b, v12
	v_mul_f32_e32 v14, 0xbfb8aa3b, v15
	s_add_u32 s0, s36, s16
	v_exp_f32_e32 v13, v13
	v_exp_f32_e32 v14, v14
	s_addc_u32 s1, s37, 0
	v_cvt_pk_bf16_f32 v5, v10, v11
	v_lshlrev_b64 v[10:11], 12, v[138:139]
	v_lshl_add_u64 v[10:11], s[0:1], 0, v[10:11]
	v_lshl_add_u64 v[10:11], v[10:11], 0, v[140:141]
	global_store_dwordx4 v[10:11], v[2:5], off
	v_and_b32_e32 v11, 0xffff0000, v91
	s_waitcnt lgkmcnt(0)
	v_lshlrev_b32_e32 v10, 16, v7
	v_add_f32_e32 v2, 1.0, v13
	v_add_f32_e32 v3, 1.0, v14
	v_rcp_f32_e32 v2, v2
	v_rcp_f32_e32 v3, v3
	v_and_b32_e32 v13, 0xffff0000, v6
	v_lshlrev_b32_e32 v14, 16, v6
	v_pk_mul_f32 v[4:5], v[14:15], v[12:13]
	v_mul_f32_e32 v6, 0xbfb8aa3b, v11
	v_pk_mul_f32 v[2:3], v[2:3], v[4:5]
	v_lshlrev_b32_e32 v4, 16, v91
	v_mul_f32_e32 v5, 0xbfb8aa3b, v4
	v_exp_f32_e32 v5, v5
	v_exp_f32_e32 v6, v6
	v_cvt_pk_bf16_f32 v2, v2, v3
	v_lshlrev_b32_e32 v0, 4, v0
	v_add_f32_e32 v3, 1.0, v5
	v_rcp_f32_e32 v12, v3
	v_add_f32_e32 v3, 1.0, v6
	v_and_b32_e32 v5, 0xffff0000, v7
	v_lshlrev_b32_e32 v6, 16, v92
	v_rcp_f32_e32 v13, v3
	v_pk_mul_f32 v[4:5], v[10:11], v[4:5]
	v_and_b32_e32 v11, 0xffff0000, v92
	v_mul_f32_e32 v3, 0xbfb8aa3b, v6
	v_exp_f32_e32 v7, v3
	v_mul_f32_e32 v3, 0xbfb8aa3b, v11
	v_exp_f32_e32 v10, v3
	v_pk_mul_f32 v[4:5], v[12:13], v[4:5]
	v_mov_b32_e32 v28, v255
	v_cvt_pk_bf16_f32 v3, v4, v5
	v_add_f32_e32 v4, 1.0, v7
	v_add_f32_e32 v5, 1.0, v10
	v_rcp_f32_e32 v4, v4
	v_rcp_f32_e32 v5, v5
	v_and_b32_e32 v7, 0xffff0000, v8
	v_lshlrev_b32_e32 v10, 16, v8
	v_pk_mul_f32 v[6:7], v[10:11], v[6:7]
	v_and_b32_e32 v11, 0xffff0000, v93
	v_pk_mul_f32 v[4:5], v[4:5], v[6:7]
	v_lshlrev_b32_e32 v6, 16, v93
	v_mul_f32_e32 v7, 0xbfb8aa3b, v6
	v_exp_f32_e32 v7, v7
	v_mul_f32_e32 v8, 0xbfb8aa3b, v11
	v_exp_f32_e32 v8, v8
	v_cvt_pk_bf16_f32 v4, v4, v5
	v_add_f32_e32 v5, 1.0, v7
	v_rcp_f32_e32 v12, v5
	v_add_f32_e32 v5, 1.0, v8
	v_rcp_f32_e32 v13, v5
	v_and_b32_e32 v7, 0xffff0000, v9
	v_lshlrev_b32_e32 v10, 16, v9
	v_pk_mul_f32 v[6:7], v[10:11], v[6:7]
	s_waitcnt vmcnt(6)
	v_lshlrev_b32_e32 v10, 16, v86
	v_pk_mul_f32 v[6:7], v[12:13], v[6:7]
	v_and_b32_e32 v13, 0xffff0000, v86
	v_cvt_pk_bf16_f32 v5, v6, v7
	v_lshlrev_b64 v[6:7], 12, v[132:133]
	v_lshl_add_u64 v[6:7], s[0:1], 0, v[6:7]
	v_lshl_add_u64 v[6:7], v[6:7], 0, v[134:135]
	global_store_dwordx4 v[6:7], v[2:5], off
	s_lshl_b32 s27, s50, 8
	s_or_b32 s5, s22, s27
	v_mul_lo_u32 v2, v136, s45
	v_lshlrev_b32_e32 v3, 4, v143
	v_add3_u32 v2, s4, v2, v3
	v_mul_f32_e32 v3, 0xbfb8aa3b, v10
	v_exp_f32_e32 v6, v3
	v_mul_f32_e32 v3, 0xbfb8aa3b, v13
	v_exp_f32_e32 v7, v3
	ds_read_b128 v[2:5], v2
	v_add_f32_e32 v6, 1.0, v6
	v_rcp_f32_e32 v14, v6
	v_add_f32_e32 v6, 1.0, v7
	v_rcp_f32_e32 v15, v6
	v_mul_lo_u32 v6, v130, s45
	v_lshlrev_b32_e32 v7, 4, v137
	v_add3_u32 v6, s4, v6, v7
	ds_read_b128 v[6:9], v6
	s_waitcnt lgkmcnt(1)
	v_and_b32_e32 v11, 0xffff0000, v2
	v_lshlrev_b32_e32 v12, 16, v2
	v_pk_mul_f32 v[10:11], v[12:13], v[10:11]
	v_lshlrev_b32_e32 v12, 16, v87
	v_pk_mul_f32 v[10:11], v[14:15], v[10:11]
	v_and_b32_e32 v15, 0xffff0000, v87
	v_mul_f32_e32 v2, 0xbfb8aa3b, v12
	v_exp_f32_e32 v13, v2
	v_mul_f32_e32 v2, 0xbfb8aa3b, v15
	v_exp_f32_e32 v14, v2
	v_cvt_pk_bf16_f32 v2, v10, v11
	v_add_f32_e32 v10, 1.0, v13
	v_rcp_f32_e32 v10, v10
	v_add_f32_e32 v11, 1.0, v14
	v_rcp_f32_e32 v11, v11
	v_and_b32_e32 v13, 0xffff0000, v3
	v_lshlrev_b32_e32 v14, 16, v3
	v_pk_mul_f32 v[12:13], v[14:15], v[12:13]
	v_and_b32_e32 v15, 0xffff0000, v88
	v_pk_mul_f32 v[10:11], v[10:11], v[12:13]
	v_lshlrev_b32_e32 v12, 16, v88
	v_mul_f32_e32 v3, 0xbfb8aa3b, v12
	v_exp_f32_e32 v13, v3
	v_mul_f32_e32 v3, 0xbfb8aa3b, v15
	v_exp_f32_e32 v14, v3
	v_cvt_pk_bf16_f32 v3, v10, v11
	v_add_f32_e32 v10, 1.0, v13
	v_rcp_f32_e32 v10, v10
	v_add_f32_e32 v11, 1.0, v14
	v_rcp_f32_e32 v11, v11
	v_and_b32_e32 v13, 0xffff0000, v4
	v_lshlrev_b32_e32 v14, 16, v4
	v_pk_mul_f32 v[12:13], v[14:15], v[12:13]
	v_and_b32_e32 v15, 0xffff0000, v89
	v_pk_mul_f32 v[10:11], v[10:11], v[12:13]
	v_lshlrev_b32_e32 v12, 16, v89
	v_mul_f32_e32 v4, 0xbfb8aa3b, v12
	v_exp_f32_e32 v13, v4
	v_mul_f32_e32 v4, 0xbfb8aa3b, v15
	v_exp_f32_e32 v14, v4
	v_cvt_pk_bf16_f32 v4, v10, v11
	v_add_f32_e32 v10, 1.0, v13
	v_rcp_f32_e32 v10, v10
	v_add_f32_e32 v11, 1.0, v14
	v_rcp_f32_e32 v11, v11
	v_and_b32_e32 v13, 0xffff0000, v5
	v_lshlrev_b32_e32 v14, 16, v5
	v_pk_mul_f32 v[12:13], v[14:15], v[12:13]
	s_waitcnt vmcnt(6)
	v_and_b32_e32 v15, 0xffff0000, v82
	v_pk_mul_f32 v[10:11], v[10:11], v[12:13]
	v_lshlrev_b32_e32 v12, 16, v82
	v_mul_f32_e32 v13, 0xbfb8aa3b, v12
	v_mul_f32_e32 v14, 0xbfb8aa3b, v15
	v_exp_f32_e32 v13, v13
	v_exp_f32_e32 v14, v14
	v_cvt_pk_bf16_f32 v5, v10, v11
	v_lshlrev_b64 v[10:11], 12, v[126:127]
	v_lshl_add_u64 v[10:11], s[0:1], 0, v[10:11]
	v_lshl_add_u64 v[10:11], v[10:11], 0, v[128:129]
	global_store_dwordx4 v[10:11], v[2:5], off
	v_and_b32_e32 v11, 0xffff0000, v83
	s_waitcnt lgkmcnt(0)
	v_lshlrev_b32_e32 v10, 16, v7
	v_add_f32_e32 v2, 1.0, v13
	v_add_f32_e32 v3, 1.0, v14
	v_rcp_f32_e32 v2, v2
	v_rcp_f32_e32 v3, v3
	v_and_b32_e32 v13, 0xffff0000, v6
	v_lshlrev_b32_e32 v14, 16, v6
	v_pk_mul_f32 v[4:5], v[14:15], v[12:13]
	v_mul_f32_e32 v6, 0xbfb8aa3b, v11
	v_pk_mul_f32 v[2:3], v[2:3], v[4:5]
	v_lshlrev_b32_e32 v4, 16, v83
	v_mul_f32_e32 v5, 0xbfb8aa3b, v4
	v_exp_f32_e32 v5, v5
	v_exp_f32_e32 v6, v6
	v_cvt_pk_bf16_f32 v2, v2, v3
	s_lshl_b32 s33, s50, 2
	v_add_f32_e32 v3, 1.0, v5
	v_rcp_f32_e32 v12, v3
	v_add_f32_e32 v3, 1.0, v6
	v_and_b32_e32 v5, 0xffff0000, v7
	v_lshlrev_b32_e32 v6, 16, v84
	v_rcp_f32_e32 v13, v3
	v_pk_mul_f32 v[4:5], v[10:11], v[4:5]
	v_and_b32_e32 v11, 0xffff0000, v84
	v_mul_f32_e32 v3, 0xbfb8aa3b, v6
	v_exp_f32_e32 v7, v3
	v_mul_f32_e32 v3, 0xbfb8aa3b, v11
	v_exp_f32_e32 v10, v3
	v_pk_mul_f32 v[4:5], v[12:13], v[4:5]
	s_mov_b32 s24, 0
	v_cvt_pk_bf16_f32 v3, v4, v5
	v_add_f32_e32 v4, 1.0, v7
	v_add_f32_e32 v5, 1.0, v10
	v_rcp_f32_e32 v4, v4
	v_rcp_f32_e32 v5, v5
	v_and_b32_e32 v7, 0xffff0000, v8
	v_lshlrev_b32_e32 v10, 16, v8
	v_pk_mul_f32 v[6:7], v[10:11], v[6:7]
	v_and_b32_e32 v11, 0xffff0000, v85
	v_pk_mul_f32 v[4:5], v[4:5], v[6:7]
	v_lshlrev_b32_e32 v6, 16, v85
	v_mul_f32_e32 v7, 0xbfb8aa3b, v6
	v_exp_f32_e32 v7, v7
	v_mul_f32_e32 v8, 0xbfb8aa3b, v11
	v_exp_f32_e32 v8, v8
	v_cvt_pk_bf16_f32 v4, v4, v5
	v_add_f32_e32 v5, 1.0, v7
	v_rcp_f32_e32 v12, v5
	v_add_f32_e32 v5, 1.0, v8
	v_rcp_f32_e32 v13, v5
	v_and_b32_e32 v7, 0xffff0000, v9
	v_lshlrev_b32_e32 v10, 16, v9
	v_pk_mul_f32 v[6:7], v[10:11], v[6:7]
	s_waitcnt vmcnt(6)
	v_lshlrev_b32_e32 v10, 16, v78
	v_pk_mul_f32 v[6:7], v[12:13], v[6:7]
	v_and_b32_e32 v13, 0xffff0000, v78
	v_cvt_pk_bf16_f32 v5, v6, v7
	v_lshlrev_b64 v[6:7], 12, v[120:121]
	v_lshl_add_u64 v[6:7], s[0:1], 0, v[6:7]
	v_lshl_add_u64 v[6:7], v[6:7], 0, v[122:123]
	global_store_dwordx4 v[6:7], v[2:5], off
	s_mov_b32 s25, 2
	s_mov_b32 s26, 63
	v_mul_lo_u32 v2, v124, s45
	v_lshlrev_b32_e32 v3, 4, v131
	v_add3_u32 v2, s4, v2, v3
	v_mul_f32_e32 v3, 0xbfb8aa3b, v10
	v_exp_f32_e32 v6, v3
	v_mul_f32_e32 v3, 0xbfb8aa3b, v13
	v_exp_f32_e32 v7, v3
	ds_read_b128 v[2:5], v2
	v_add_f32_e32 v6, 1.0, v6
	v_rcp_f32_e32 v14, v6
	v_add_f32_e32 v6, 1.0, v7
	v_rcp_f32_e32 v15, v6
	v_mul_lo_u32 v6, v118, s45
	v_lshlrev_b32_e32 v7, 4, v125
	v_add3_u32 v6, s4, v6, v7
	ds_read_b128 v[6:9], v6
	s_waitcnt lgkmcnt(1)
	v_and_b32_e32 v11, 0xffff0000, v2
	v_lshlrev_b32_e32 v12, 16, v2
	v_pk_mul_f32 v[10:11], v[12:13], v[10:11]
	v_lshlrev_b32_e32 v12, 16, v79
	v_pk_mul_f32 v[10:11], v[14:15], v[10:11]
	v_and_b32_e32 v15, 0xffff0000, v79
	v_mul_f32_e32 v2, 0xbfb8aa3b, v12
	v_exp_f32_e32 v13, v2
	v_mul_f32_e32 v2, 0xbfb8aa3b, v15
	v_exp_f32_e32 v14, v2
	v_cvt_pk_bf16_f32 v2, v10, v11
	v_add_f32_e32 v10, 1.0, v13
	v_rcp_f32_e32 v10, v10
	v_add_f32_e32 v11, 1.0, v14
	v_rcp_f32_e32 v11, v11
	v_and_b32_e32 v13, 0xffff0000, v3
	v_lshlrev_b32_e32 v14, 16, v3
	v_pk_mul_f32 v[12:13], v[14:15], v[12:13]
	v_and_b32_e32 v15, 0xffff0000, v80
	v_pk_mul_f32 v[10:11], v[10:11], v[12:13]
	v_lshlrev_b32_e32 v12, 16, v80
	v_mul_f32_e32 v3, 0xbfb8aa3b, v12
	v_exp_f32_e32 v13, v3
	v_mul_f32_e32 v3, 0xbfb8aa3b, v15
	v_exp_f32_e32 v14, v3
	v_cvt_pk_bf16_f32 v3, v10, v11
	v_add_f32_e32 v10, 1.0, v13
	v_rcp_f32_e32 v10, v10
	v_add_f32_e32 v11, 1.0, v14
	v_rcp_f32_e32 v11, v11
	v_and_b32_e32 v13, 0xffff0000, v4
	v_lshlrev_b32_e32 v14, 16, v4
	v_pk_mul_f32 v[12:13], v[14:15], v[12:13]
	v_and_b32_e32 v15, 0xffff0000, v81
	v_pk_mul_f32 v[10:11], v[10:11], v[12:13]
	v_lshlrev_b32_e32 v12, 16, v81
	v_mul_f32_e32 v4, 0xbfb8aa3b, v12
	v_exp_f32_e32 v13, v4
	v_mul_f32_e32 v4, 0xbfb8aa3b, v15
	v_exp_f32_e32 v14, v4
	v_cvt_pk_bf16_f32 v4, v10, v11
	v_add_f32_e32 v10, 1.0, v13
	v_rcp_f32_e32 v10, v10
	v_add_f32_e32 v11, 1.0, v14
	v_rcp_f32_e32 v11, v11
	v_and_b32_e32 v13, 0xffff0000, v5
	v_lshlrev_b32_e32 v14, 16, v5
	v_pk_mul_f32 v[12:13], v[14:15], v[12:13]
	s_waitcnt vmcnt(6)
	v_and_b32_e32 v15, 0xffff0000, v74
	v_pk_mul_f32 v[10:11], v[10:11], v[12:13]
	v_lshlrev_b32_e32 v12, 16, v74
	v_mul_f32_e32 v13, 0xbfb8aa3b, v12
	v_mul_f32_e32 v14, 0xbfb8aa3b, v15
	v_exp_f32_e32 v13, v13
	v_exp_f32_e32 v14, v14
	v_cvt_pk_bf16_f32 v5, v10, v11
	v_lshlrev_b64 v[10:11], 12, v[114:115]
	v_lshl_add_u64 v[10:11], s[0:1], 0, v[10:11]
	v_lshl_add_u64 v[10:11], v[10:11], 0, v[116:117]
	global_store_dwordx4 v[10:11], v[2:5], off
	v_and_b32_e32 v11, 0xffff0000, v75
	s_waitcnt lgkmcnt(0)
	v_lshlrev_b32_e32 v10, 16, v7
	v_add_f32_e32 v2, 1.0, v13
	v_add_f32_e32 v3, 1.0, v14
	v_rcp_f32_e32 v2, v2
	v_rcp_f32_e32 v3, v3
	v_and_b32_e32 v13, 0xffff0000, v6
	v_lshlrev_b32_e32 v14, 16, v6
	v_pk_mul_f32 v[4:5], v[14:15], v[12:13]
	v_mul_f32_e32 v6, 0xbfb8aa3b, v11
	v_pk_mul_f32 v[2:3], v[2:3], v[4:5]
	v_lshlrev_b32_e32 v4, 16, v75
	v_mul_f32_e32 v5, 0xbfb8aa3b, v4
	v_exp_f32_e32 v5, v5
	v_exp_f32_e32 v6, v6
	v_cvt_pk_bf16_f32 v2, v2, v3
	v_mov_b32_e32 v196, 0
	v_add_f32_e32 v3, 1.0, v5
	v_rcp_f32_e32 v12, v3
	v_add_f32_e32 v3, 1.0, v6
	v_and_b32_e32 v5, 0xffff0000, v7
	v_lshlrev_b32_e32 v6, 16, v76
	v_rcp_f32_e32 v13, v3
	v_pk_mul_f32 v[4:5], v[10:11], v[4:5]
	v_and_b32_e32 v11, 0xffff0000, v76
	v_mul_f32_e32 v3, 0xbfb8aa3b, v6
	v_exp_f32_e32 v7, v3
	v_mul_f32_e32 v3, 0xbfb8aa3b, v11
	v_exp_f32_e32 v10, v3
	v_pk_mul_f32 v[4:5], v[12:13], v[4:5]
	v_mov_b32_e32 v197, 0xf149f2ca
	v_cvt_pk_bf16_f32 v3, v4, v5
	v_add_f32_e32 v4, 1.0, v7
	v_add_f32_e32 v5, 1.0, v10
	v_rcp_f32_e32 v4, v4
	v_rcp_f32_e32 v5, v5
	v_and_b32_e32 v7, 0xffff0000, v8
	v_lshlrev_b32_e32 v10, 16, v8
	v_pk_mul_f32 v[6:7], v[10:11], v[6:7]
	v_and_b32_e32 v11, 0xffff0000, v77
	v_pk_mul_f32 v[4:5], v[4:5], v[6:7]
	v_lshlrev_b32_e32 v6, 16, v77
	v_mul_f32_e32 v7, 0xbfb8aa3b, v6
	v_exp_f32_e32 v7, v7
	v_mul_f32_e32 v8, 0xbfb8aa3b, v11
	v_exp_f32_e32 v8, v8
	v_cvt_pk_bf16_f32 v4, v4, v5
	v_add_f32_e32 v5, 1.0, v7
	v_rcp_f32_e32 v12, v5
	v_add_f32_e32 v5, 1.0, v8
	v_rcp_f32_e32 v13, v5
	v_and_b32_e32 v7, 0xffff0000, v9
	v_lshlrev_b32_e32 v10, 16, v9
	v_pk_mul_f32 v[6:7], v[10:11], v[6:7]
	s_waitcnt vmcnt(6)
	v_lshlrev_b32_e32 v10, 16, v70
	v_pk_mul_f32 v[6:7], v[12:13], v[6:7]
	v_and_b32_e32 v13, 0xffff0000, v70
	v_cvt_pk_bf16_f32 v5, v6, v7
	v_lshlrev_b64 v[6:7], 12, v[108:109]
	v_lshl_add_u64 v[6:7], s[0:1], 0, v[6:7]
	v_lshl_add_u64 v[6:7], v[6:7], 0, v[110:111]
	global_store_dwordx4 v[6:7], v[2:5], off
	s_nop 1
	v_mul_lo_u32 v2, v112, s45
	v_lshlrev_b32_e32 v3, 4, v119
	v_add3_u32 v2, s4, v2, v3
	v_mul_f32_e32 v3, 0xbfb8aa3b, v10
	v_exp_f32_e32 v6, v3
	v_mul_f32_e32 v3, 0xbfb8aa3b, v13
	v_exp_f32_e32 v7, v3
	ds_read_b128 v[2:5], v2
	v_add_f32_e32 v6, 1.0, v6
	v_rcp_f32_e32 v14, v6
	v_add_f32_e32 v6, 1.0, v7
	v_rcp_f32_e32 v15, v6
	v_mul_lo_u32 v6, v106, s45
	v_add3_u32 v0, s4, v6, v0
	ds_read_b128 v[6:9], v0
	s_waitcnt lgkmcnt(1)
	v_and_b32_e32 v11, 0xffff0000, v2
	v_lshlrev_b32_e32 v12, 16, v2
	v_pk_mul_f32 v[10:11], v[12:13], v[10:11]
	v_lshlrev_b32_e32 v12, 16, v71
	v_pk_mul_f32 v[10:11], v[14:15], v[10:11]
	v_and_b32_e32 v15, 0xffff0000, v71
	v_mul_f32_e32 v0, 0xbfb8aa3b, v12
	v_exp_f32_e32 v0, v0
	v_mul_f32_e32 v2, 0xbfb8aa3b, v15
	v_exp_f32_e32 v13, v2
	v_cvt_pk_bf16_f32 v2, v10, v11
	v_add_f32_e32 v0, 1.0, v0
	v_rcp_f32_e32 v10, v0
	v_add_f32_e32 v0, 1.0, v13
	v_rcp_f32_e32 v11, v0
	v_and_b32_e32 v13, 0xffff0000, v3
	v_lshlrev_b32_e32 v14, 16, v3
	v_pk_mul_f32 v[12:13], v[14:15], v[12:13]
	v_and_b32_e32 v15, 0xffff0000, v72
	v_pk_mul_f32 v[10:11], v[10:11], v[12:13]
	v_lshlrev_b32_e32 v12, 16, v72
	v_mul_f32_e32 v0, 0xbfb8aa3b, v12
	v_exp_f32_e32 v0, v0
	v_mul_f32_e32 v3, 0xbfb8aa3b, v15
	v_exp_f32_e32 v13, v3
	v_cvt_pk_bf16_f32 v3, v10, v11
	v_add_f32_e32 v0, 1.0, v0
	v_rcp_f32_e32 v10, v0
	v_add_f32_e32 v0, 1.0, v13
	v_rcp_f32_e32 v11, v0
	v_and_b32_e32 v13, 0xffff0000, v4
	v_lshlrev_b32_e32 v14, 16, v4
	v_pk_mul_f32 v[12:13], v[14:15], v[12:13]
	v_and_b32_e32 v15, 0xffff0000, v73
	v_pk_mul_f32 v[10:11], v[10:11], v[12:13]
	v_lshlrev_b32_e32 v12, 16, v73
	v_mul_f32_e32 v0, 0xbfb8aa3b, v12
	v_exp_f32_e32 v0, v0
	v_mul_f32_e32 v4, 0xbfb8aa3b, v15
	v_exp_f32_e32 v13, v4
	v_cvt_pk_bf16_f32 v4, v10, v11
	v_add_f32_e32 v0, 1.0, v0
	v_rcp_f32_e32 v10, v0
	v_add_f32_e32 v0, 1.0, v13
	v_rcp_f32_e32 v11, v0
	v_and_b32_e32 v13, 0xffff0000, v5
	v_lshlrev_b32_e32 v14, 16, v5
	v_pk_mul_f32 v[12:13], v[14:15], v[12:13]
	s_waitcnt vmcnt(6)
	v_and_b32_e32 v15, 0xffff0000, v66
	v_pk_mul_f32 v[10:11], v[10:11], v[12:13]
	v_lshlrev_b32_e32 v12, 16, v66
	v_mul_f32_e32 v0, 0xbfb8aa3b, v12
	v_exp_f32_e32 v0, v0
	v_mul_f32_e32 v13, 0xbfb8aa3b, v15
	v_exp_f32_e32 v13, v13
	v_cvt_pk_bf16_f32 v5, v10, v11
	v_lshlrev_b64 v[10:11], 12, v[102:103]
	v_lshl_add_u64 v[10:11], s[0:1], 0, v[10:11]
	v_lshl_add_u64 v[10:11], v[10:11], 0, v[104:105]
	v_add_f32_e32 v0, 1.0, v0
	global_store_dwordx4 v[10:11], v[2:5], off
	s_waitcnt lgkmcnt(0)
	v_lshlrev_b32_e32 v14, 16, v6
	v_and_b32_e32 v11, 0xffff0000, v67
	v_rcp_f32_e32 v2, v0
	v_add_f32_e32 v0, 1.0, v13
	v_rcp_f32_e32 v3, v0
	v_and_b32_e32 v13, 0xffff0000, v6
	v_pk_mul_f32 v[4:5], v[14:15], v[12:13]
	v_lshlrev_b32_e32 v10, 16, v7
	v_pk_mul_f32 v[2:3], v[2:3], v[4:5]
	v_lshlrev_b32_e32 v4, 16, v67
	v_mul_f32_e32 v0, 0xbfb8aa3b, v4
	v_exp_f32_e32 v0, v0
	v_mul_f32_e32 v5, 0xbfb8aa3b, v11
	v_exp_f32_e32 v5, v5
	v_lshlrev_b32_e32 v6, 16, v68
	v_add_f32_e32 v0, 1.0, v0
	v_rcp_f32_e32 v12, v0
	v_add_f32_e32 v0, 1.0, v5
	v_and_b32_e32 v5, 0xffff0000, v7
	v_rcp_f32_e32 v13, v0
	v_pk_mul_f32 v[4:5], v[10:11], v[4:5]
	v_and_b32_e32 v11, 0xffff0000, v68
	v_mul_f32_e32 v0, 0xbfb8aa3b, v6
	v_cvt_pk_bf16_f32 v2, v2, v3
	v_exp_f32_e32 v0, v0
	v_mul_f32_e32 v3, 0xbfb8aa3b, v11
	v_exp_f32_e32 v7, v3
	v_pk_mul_f32 v[4:5], v[12:13], v[4:5]
	v_add_f32_e32 v0, 1.0, v0
	v_cvt_pk_bf16_f32 v3, v4, v5
	v_rcp_f32_e32 v4, v0
	v_add_f32_e32 v0, 1.0, v7
	v_rcp_f32_e32 v5, v0
	v_and_b32_e32 v7, 0xffff0000, v8
	v_lshlrev_b32_e32 v10, 16, v8
	v_pk_mul_f32 v[6:7], v[10:11], v[6:7]
	v_and_b32_e32 v11, 0xffff0000, v69
	v_pk_mul_f32 v[4:5], v[4:5], v[6:7]
	v_lshlrev_b32_e32 v6, 16, v69
	v_mul_f32_e32 v0, 0xbfb8aa3b, v6
	v_exp_f32_e32 v0, v0
	v_mul_f32_e32 v7, 0xbfb8aa3b, v11
	v_exp_f32_e32 v7, v7
	v_lshlrev_b32_e32 v10, 16, v9
	v_add_f32_e32 v0, 1.0, v0
	v_rcp_f32_e32 v12, v0
	v_add_f32_e32 v0, 1.0, v7
	v_rcp_f32_e32 v13, v0
	v_and_b32_e32 v7, 0xffff0000, v9
	v_pk_mul_f32 v[6:7], v[10:11], v[6:7]
	v_cvt_pk_bf16_f32 v4, v4, v5
	v_pk_mul_f32 v[6:7], v[12:13], v[6:7]
	s_nop 0
	v_cvt_pk_bf16_f32 v5, v6, v7
	v_lshlrev_b64 v[6:7], 12, v[98:99]
	v_lshl_add_u64 v[6:7], s[0:1], 0, v[6:7]
	v_lshl_add_u64 v[6:7], v[6:7], 0, v[100:101]
	global_store_dwordx4 v[6:7], v[2:5], off
	s_barrier
	s_nop 0
	v_ashrrev_i32_e32 v0, 31, v28
	v_lshrrev_b32_e32 v0, 28, v0
	v_add_u32_e32 v0, v28, v0
	v_ashrrev_i32_e32 v146, 4, v0
	v_and_b32_e32 v0, -16, v0
	v_sub_u32_e32 v29, v28, v0
	v_ashrrev_i32_e32 v147, 31, v146
	v_lshlrev_b32_e32 v4, 3, v29
	v_lshlrev_b64 v[2:3], 14, v[146:147]
	v_ashrrev_i32_e32 v5, 31, v4
	v_lshl_add_u64 v[2:3], s[20:21], 0, v[2:3]
	v_lshlrev_b64 v[18:19], 1, v[4:5]
	v_lshl_add_u64 v[20:21], v[2:3], 0, v[18:19]
	v_add_co_u32_e32 v6, vcc, s43, v20
	v_add_u32_e32 v0, 0x200, v28
	s_nop 0
	v_addc_co_u32_e32 v7, vcc, 0, v21, vcc
	global_load_dwordx4 v[2:5], v[6:7], off offset:-4096
	s_nop 0
	global_load_dwordx4 v[6:9], v[6:7], off
	v_ashrrev_i32_e32 v10, 31, v0
	v_readfirstlane_b32 s4, v28
	v_lshrrev_b32_e32 v10, 28, v10
	s_ashr_i32 s22, s4, 1
	v_add_u32_e32 v10, v0, v10
	s_andn2_b32 s22, s22, 31
	v_ashrrev_i32_e32 v148, 4, v10
	v_and_b32_e32 v10, -16, v10
	s_ashr_i32 s34, s22, 31
	v_sub_u32_e32 v30, v0, v10
	s_add_u32 s4, s5, s22
	v_ashrrev_i32_e32 v149, 31, v148
	v_lshlrev_b32_e32 v12, 3, v30
	v_and_b32_e32 v31, 31, v28
	s_addc_u32 s5, s23, s34
	v_lshlrev_b64 v[10:11], 14, v[148:149]
	v_ashrrev_i32_e32 v13, 31, v12
	v_or_b32_e32 v26, s4, v31
	v_mov_b32_e32 v27, s5
	v_lshl_add_u64 v[10:11], s[20:21], 0, v[10:11]
	v_lshlrev_b64 v[22:23], 1, v[12:13]
	v_lshlrev_b64 v[26:27], 14, v[26:27]
	v_lshl_add_u64 v[24:25], v[10:11], 0, v[22:23]
	v_bfe_u32 v32, v28, 5, 1
	v_lshl_add_u64 v[26:27], s[12:13], 0, v[26:27]
	v_add_co_u32_e32 v14, vcc, s43, v24
	v_lshl_add_u64 v[26:27], v[26:27], 0, s[16:17]
	v_lshlrev_b32_e32 v0, 4, v32
	v_addc_co_u32_e32 v15, vcc, 0, v25, vcc
	v_lshl_add_u64 v[26:27], v[26:27], 0, v[0:1]
	v_mul_lo_u32 v149, v146, s45
	v_lshlrev_b32_e32 v156, 4, v29
	global_load_dwordx4 v[10:13], v[14:15], off offset:-4096
	s_nop 0
	global_load_dwordx4 v[14:17], v[14:15], off
	s_nop 0
	global_load_dwordx4 v[98:101], v[26:27], off
	global_load_dwordx4 v[102:105], v[26:27], off offset:32
	global_load_dwordx4 v[106:109], v[26:27], off offset:64
	global_load_dwordx4 v[110:113], v[26:27], off offset:96
	global_load_dwordx4 v[114:117], v[26:27], off offset:128
	global_load_dwordx4 v[118:121], v[26:27], off offset:160
	global_load_dwordx4 v[122:125], v[26:27], off offset:192
	global_load_dwordx4 v[126:129], v[26:27], off offset:224
	v_add3_u32 v26, 0, v149, v156
	s_waitcnt vmcnt(0)
	v_mul_lo_u32 v158, v148, s45
	v_lshlrev_b32_e32 v159, 4, v30
	v_lshlrev_b32_e32 v163, 2, v32
	v_add_u32_e32 v161, 0, v0
	s_add_i32 s7, s7, s22
	v_and_b32_e32 v147, 63, v28
	v_mad_u32_u24 v162, v31, s45, v161
	v_lshl_add_u32 v150, v146, 14, v18
	s_mov_b64 s[78:79], s[20:21]
	v_lshl_add_u32 v152, v148, 14, v22
	v_or_b32_e32 v195, s7, v31
	s_add_i32 s23, s33, 4
	v_mul_lo_u32 v157, v146, s46
	v_mul_lo_u32 v160, v148, s46
	s_add_i32 s27, s22, s27
	s_or_b32 s33, s33, 3
	v_or_b32_e32 v165, 32, v163
	v_or_b32_e32 v166, 33, v163
	v_or_b32_e32 v167, 2, v163
	v_or_b32_e32 v168, 34, v163
	v_or_b32_e32 v169, 3, v163
	v_or_b32_e32 v170, 35, v163
	v_or_b32_e32 v171, 8, v163
	v_or_b32_e32 v172, 40, v163
	v_or_b32_e32 v173, 9, v163
	v_or_b32_e32 v174, 41, v163
	v_or_b32_e32 v175, 10, v163
	v_or_b32_e32 v176, 42, v163
	v_or_b32_e32 v177, 11, v163
	v_or_b32_e32 v178, 43, v163
	v_or_b32_e32 v179, 16, v163
	v_or_b32_e32 v180, 48, v163
	v_or_b32_e32 v181, 17, v163
	v_or_b32_e32 v182, 49, v163
	v_or_b32_e32 v183, 18, v163
	v_or_b32_e32 v184, 50, v163
	v_or_b32_e32 v185, 19, v163
	v_or_b32_e32 v186, 51, v163
	v_or_b32_e32 v187, 24, v163
	v_or_b32_e32 v188, 56, v163
	ds_write_b128 v26, v[2:5]
	v_mad_u64_u32 v[2:3], s[34:35], v146, 48, v[26:27]
	ds_write_b128 v2, v[6:9] offset:34816
	v_add_co_u32_e32 v2, vcc, s47, v20
	v_mov_b32_e32 v4, v1
	s_nop 0
	v_addc_co_u32_e32 v3, vcc, 0, v21, vcc
	global_load_dwordx4 v[130:133], v[2:3], off offset:-4096
	global_load_dwordx4 v[134:137], v[2:3], off
	v_add_co_u32_e32 v2, vcc, s47, v24
	v_mov_b32_e32 v5, v1
	s_nop 0
	v_addc_co_u32_e32 v3, vcc, 0, v25, vcc
	global_load_dwordx4 v[138:141], v[2:3], off offset:-4096
	global_load_dwordx4 v[142:145], v[2:3], off
	v_add3_u32 v2, 0, v158, v159
	v_mov_b32_e32 v6, v1
	v_mov_b32_e32 v7, v1
	v_mov_b32_e32 v8, v1
	v_mov_b32_e32 v9, v1
	v_or_b32_e32 v189, 25, v163
	v_or_b32_e32 v190, 57, v163
	v_or_b32_e32 v191, 26, v163
	v_or_b32_e32 v192, 58, v163
	v_or_b32_e32 v193, 27, v163
	v_or_b32_e32 v194, 59, v163
	ds_write_b128 v2, v[10:13]
	v_mad_u64_u32 v[2:3], s[34:35], v148, 48, v[2:3]
	ds_write_b128 v2, v[14:17] offset:34816
	v_lshrrev_b32_e32 v2, 2, v28
	v_and_or_b32 v0, v2, 3, v163
	v_lshlrev_b32_e32 v2, 1, v28
	v_lshlrev_b32_e32 v3, 3, v28
	v_mad_u32_u24 v0, v0, s46, 0
	v_and_b32_e32 v2, 32, v2
	v_and_b32_e32 v3, 24, v3
	v_mov_b32_e32 v14, v1
	v_mov_b32_e32 v15, v1
	v_add3_u32 v164, v0, v2, v3
	v_mov_b32_e32 v0, v1
	v_mov_b32_e32 v2, v1
	v_mov_b32_e32 v3, v1
	v_mov_b32_e32 v10, v1
	v_mov_b32_e32 v11, v1
	v_mov_b32_e32 v12, v1
	v_mov_b32_e32 v13, v1
	v_mov_b64_e32 v[64:65], v[14:15]
	v_mov_b64_e32 v[48:49], v[14:15]
	v_mov_b64_e32 v[32:33], v[14:15]
	v_mov_b64_e32 v[62:63], v[12:13]
	v_mov_b64_e32 v[60:61], v[10:11]
	v_mov_b64_e32 v[58:59], v[8:9]
	v_mov_b64_e32 v[56:57], v[6:7]
	v_mov_b64_e32 v[54:55], v[4:5]
	v_mov_b64_e32 v[52:53], v[2:3]
	v_mov_b64_e32 v[50:51], v[0:1]
	v_mov_b64_e32 v[46:47], v[12:13]
	v_mov_b64_e32 v[44:45], v[10:11]
	v_mov_b64_e32 v[42:43], v[8:9]
	v_mov_b64_e32 v[40:41], v[6:7]
	v_mov_b64_e32 v[38:39], v[4:5]
	v_mov_b64_e32 v[36:37], v[2:3]
	v_mov_b64_e32 v[34:35], v[0:1]
	v_mov_b64_e32 v[30:31], v[12:13]
	v_mov_b64_e32 v[28:29], v[10:11]
	v_mov_b64_e32 v[26:27], v[8:9]
	v_mov_b64_e32 v[24:25], v[6:7]
	v_mov_b64_e32 v[22:23], v[4:5]
	v_mov_b64_e32 v[20:21], v[2:3]
	v_mov_b64_e32 v[18:19], v[0:1]
	v_mov_b64_e32 v[16:17], v[14:15]
	v_mov_b64_e32 v[14:15], v[12:13]
	v_mov_b64_e32 v[12:13], v[10:11]
	v_mov_b64_e32 v[10:11], v[8:9]
	v_mov_b64_e32 v[8:9], v[6:7]
	v_mov_b64_e32 v[6:7], v[4:5]
	v_mov_b64_e32 v[4:5], v[2:3]
	v_mov_b64_e32 v[2:3], v[0:1]
	s_waitcnt lgkmcnt(0)
	s_movk_i32 s68, 0x5000
	s_mov_b32 s69, 0
	s_mov_b32 s70, 0xe800
	s_mov_b32 s72, 0
	s_barrier
	v_readfirstlane_b32 s73, v255
	s_cmp_lt_u32 s73, 0x100
	s_cbranch_scc1 .Lyp657
	s_setprio 1

.LBB0_657:
	s_add_i32 s7, s25, -2
	s_and_b32 s7, s7, 1
	s_xor_b32 s20, s7, 1
	s_mul_i32 s21, s20, 0x4400
	s_add_i32 s21, s21, 0
	s_mulk_i32 s20, 0xc00
	s_add_i32 s20, s21, s20
	v_add3_u32 v0, s21, v149, v156
	s_waitcnt vmcnt(3)
	ds_write_b128 v0, v[130:133]
	v_add3_u32 v0, s68, v157, v156
	s_waitcnt vmcnt(2)
	ds_write_b128 v0, v[134:137] offset:34816
	v_add3_u32 v0, s21, v158, v159
	s_cmp_lt_u32 s25, s23
	s_waitcnt vmcnt(1)
	ds_write_b128 v0, v[138:141]
	v_add3_u32 v0, s68, v160, v159
	s_cselect_b32 s20, s25, s33
	s_lshl_b32 s20, s20, 20
	s_add_u32 s80, s78, s20
	s_addc_u32 s81, s79, 0
	s_add_u32 s80, s80, 0x1000
	s_addc_u32 s81, s81, 0
	s_add_u32 s82, s80, 0x1000
	s_addc_u32 s83, s81, 0
	s_waitcnt vmcnt(0)
	ds_write_b128 v0, v[142:145] offset:34816
	global_load_dwordx4 v[130:133], v150, s[80:81]
	global_load_dwordx4 v[134:137], v150, s[82:83]
	s_sub_i32 s20, s26, 63
	s_cmp_gt_i32 s20, s27
	global_load_dwordx4 v[138:141], v152, s[80:81]
	global_load_dwordx4 v[142:145], v152, s[82:83]
	s_sub_i32 s20, s26, 63
	s_cmp_gt_i32 s20, s27
	s_cbranch_scc1 .Lff2a_inact
	s_cmp_eq_u32 s72, 0
	s_cbranch_scc1 .Lff2a_first
	s_mul_i32 s20, s7, 0x4400
	v_add_u32_e32 v0, s20, v162
	ds_read_b128 v[198:201], v0
	ds_read_b128 v[202:205], v0 offset:32
	ds_read_b128 v[206:209], v0 offset:8704
	ds_read_b128 v[210:213], v0 offset:8736
	v_add_u32_e32 v246, s24, v161
	v_add_u32_e32 v234, 0x12800, v246
	v_add_u32_e32 v235, 0x12880, v246
	v_add_u32_e32 v238, 0x12820, v246
	v_add_u32_e32 v239, 0x128a0, v246
	v_add_u32_e32 v242, 0x12840, v246
	v_add_u32_e32 v243, 0x128c0, v246
	v_add_u32_e32 v247, 0x12860, v246
	v_add_u32_e32 v246, 0x128e0, v246
	ds_read_b128 v[218:221], v234
	ds_read_b128 v[234:237], v235
	ds_read_b128 v[222:225], v238
	ds_read_b128 v[238:241], v239
	ds_read_b128 v[226:229], v242
	ds_read_b128 v[242:245], v243
	ds_read_b128 v[230:233], v247
	ds_read_b128 v[246:249], v246
	s_waitcnt lgkmcnt(1)
	v_mfma_f32_32x32x16_bf16 v[218:233], v[198:201], v[98:101], v[218:233]
	v_sub_f32_e32 v82, v82, v197
	v_sub_f32_e32 v83, v83, v197
	v_sub_f32_e32 v84, v84, v197
	v_sub_f32_e32 v85, v85, v197
	v_exp_f32_e32 v82, v82
	v_exp_f32_e32 v83, v83
	v_exp_f32_e32 v84, v84
	v_exp_f32_e32 v85, v85
	s_waitcnt lgkmcnt(0)
	v_mfma_f32_32x32x16_bf16 v[234:249], v[206:209], v[98:101], v[234:249]
	v_sub_f32_e32 v86, v86, v197
	v_sub_f32_e32 v87, v87, v197
	v_sub_f32_e32 v88, v88, v197
	v_sub_f32_e32 v89, v89, v197
	v_exp_f32_e32 v86, v86
	v_exp_f32_e32 v87, v87
	v_exp_f32_e32 v88, v88
	v_exp_f32_e32 v89, v89
	v_mfma_f32_32x32x16_bf16 v[218:233], v[202:205], v[102:105], v[218:233]
	v_sub_f32_e32 v66, v66, v197
	v_sub_f32_e32 v67, v67, v197
	v_sub_f32_e32 v68, v68, v197
	v_sub_f32_e32 v69, v69, v197
	v_exp_f32_e32 v66, v66
	v_exp_f32_e32 v67, v67
	v_exp_f32_e32 v68, v68
	v_exp_f32_e32 v69, v69
	ds_read_b128 v[198:201], v0 offset:64
	ds_read_b128 v[202:205], v0 offset:96
	ds_read_b128 v[206:209], v0 offset:8768
	ds_read_b128 v[214:217], v0 offset:8800
	v_mfma_f32_32x32x16_bf16 v[234:249], v[210:213], v[102:105], v[234:249]
	v_add_f32_e32 v250, v82, v86
	v_add_f32_e32 v251, v83, v87
	v_add_f32_e32 v252, v84, v88
	v_add_f32_e32 v253, v85, v89
	v_sub_f32_e32 v70, v70, v197
	v_sub_f32_e32 v71, v71, v197
	v_sub_f32_e32 v72, v72, v197
	v_sub_f32_e32 v73, v73, v197
	s_waitcnt lgkmcnt(3)
	v_mfma_f32_32x32x16_bf16 v[218:233], v[198:201], v[106:109], v[218:233]
	v_exp_f32_e32 v70, v70
	v_exp_f32_e32 v71, v71
	v_exp_f32_e32 v72, v72
	v_exp_f32_e32 v73, v73
	v_add_f32_e32 v250, v250, v66
	v_add_f32_e32 v251, v251, v67
	v_add_f32_e32 v252, v252, v68
	v_add_f32_e32 v253, v253, v69
	s_waitcnt lgkmcnt(1)
	v_mfma_f32_32x32x16_bf16 v[234:249], v[206:209], v[106:109], v[234:249]
	v_sub_f32_e32 v90, v90, v197
	v_sub_f32_e32 v91, v91, v197
	v_sub_f32_e32 v92, v92, v197
	v_sub_f32_e32 v93, v93, v197
	v_exp_f32_e32 v90, v90
	v_exp_f32_e32 v91, v91
	v_exp_f32_e32 v92, v92
	v_exp_f32_e32 v93, v93
	v_mfma_f32_32x32x16_bf16 v[218:233], v[202:205], v[110:113], v[218:233]
	v_add_f32_e32 v250, v250, v70
	v_add_f32_e32 v251, v251, v71
	v_add_f32_e32 v252, v252, v72
	v_add_f32_e32 v253, v253, v73
	v_sub_f32_e32 v94, v94, v197
	v_sub_f32_e32 v95, v95, v197
	v_sub_f32_e32 v96, v96, v197
	v_sub_f32_e32 v97, v97, v197
	ds_read_b128 v[198:201], v0 offset:128
	ds_read_b128 v[202:205], v0 offset:160
	ds_read_b128 v[206:209], v0 offset:8832
	ds_read_b128 v[210:213], v0 offset:8864
	s_waitcnt lgkmcnt(4)
	v_mfma_f32_32x32x16_bf16 v[234:249], v[214:217], v[110:113], v[234:249]
	v_exp_f32_e32 v94, v94
	v_exp_f32_e32 v95, v95
	v_exp_f32_e32 v96, v96
	v_exp_f32_e32 v97, v97
	v_add_f32_e32 v250, v250, v90
	v_add_f32_e32 v251, v251, v91
	v_add_f32_e32 v252, v252, v92
	v_add_f32_e32 v253, v253, v93
	s_waitcnt lgkmcnt(3)
	v_mfma_f32_32x32x16_bf16 v[218:233], v[198:201], v[114:117], v[218:233]
	v_sub_f32_e32 v74, v74, v197
	v_sub_f32_e32 v75, v75, v197
	v_sub_f32_e32 v76, v76, v197
	v_sub_f32_e32 v77, v77, v197
	v_exp_f32_e32 v74, v74
	v_exp_f32_e32 v75, v75
	v_exp_f32_e32 v76, v76
	v_exp_f32_e32 v77, v77
	s_waitcnt lgkmcnt(1)
	v_mfma_f32_32x32x16_bf16 v[234:249], v[206:209], v[114:117], v[234:249]
	v_add_f32_e32 v250, v250, v94
	v_add_f32_e32 v251, v251, v95
	v_add_f32_e32 v252, v252, v96
	v_add_f32_e32 v253, v253, v97
	v_sub_f32_e32 v78, v78, v197
	v_sub_f32_e32 v79, v79, v197
	v_sub_f32_e32 v80, v80, v197
	v_sub_f32_e32 v81, v81, v197
	v_mfma_f32_32x32x16_bf16 v[218:233], v[202:205], v[118:121], v[218:233]
	v_exp_f32_e32 v78, v78
	v_exp_f32_e32 v79, v79
	v_exp_f32_e32 v80, v80
	v_exp_f32_e32 v81, v81
	v_add_f32_e32 v250, v250, v74
	v_add_f32_e32 v251, v251, v75
	v_add_f32_e32 v252, v252, v76
	v_add_f32_e32 v253, v253, v77
	ds_read_b128 v[198:201], v0 offset:192
	ds_read_b128 v[202:205], v0 offset:224
	ds_read_b128 v[206:209], v0 offset:8896
	ds_read_b128 v[214:217], v0 offset:8928
	s_waitcnt lgkmcnt(4)
	v_mfma_f32_32x32x16_bf16 v[234:249], v[210:213], v[118:121], v[234:249]
	v_add_f32_e32 v250, v250, v78
	v_add_f32_e32 v251, v251, v79
	v_add_f32_e32 v252, v252, v80
	v_add_f32_e32 v253, v253, v81
	v_add_f32_e32 v250, v250, v251
	v_add_f32_e32 v252, v252, v253
	v_add_f32_e32 v250, v250, v252
	v_add_f32_e32 v196, v196, v250
	s_waitcnt lgkmcnt(3)
	v_mfma_f32_32x32x16_bf16 v[218:233], v[198:201], v[122:125], v[218:233]
	v_cvt_pk_bf16_f32 v73, v72, v73
	v_cvt_pk_bf16_f32 v72, v70, v71
	v_cvt_pk_bf16_f32 v71, v68, v69
	v_cvt_pk_bf16_f32 v70, v66, v67
	v_cvt_pk_bf16_f32 v66, v82, v83
	v_cvt_pk_bf16_f32 v67, v84, v85
	v_cvt_pk_bf16_f32 v68, v86, v87
	v_cvt_pk_bf16_f32 v69, v88, v89
	s_waitcnt lgkmcnt(1)
	v_mfma_f32_32x32x16_bf16 v[234:249], v[206:209], v[122:125], v[234:249]
	v_cvt_pk_bf16_f32 v81, v80, v81
	v_cvt_pk_bf16_f32 v80, v78, v79
	v_cvt_pk_bf16_f32 v79, v76, v77
	v_cvt_pk_bf16_f32 v78, v74, v75
	v_cvt_pk_bf16_f32 v74, v90, v91
	v_cvt_pk_bf16_f32 v75, v92, v93
	v_cvt_pk_bf16_f32 v76, v94, v95
	v_cvt_pk_bf16_f32 v77, v96, v97
	v_mfma_f32_32x32x16_bf16 v[218:233], v[202:205], v[126:129], v[218:233]
	s_waitcnt lgkmcnt(0)
	v_mfma_f32_32x32x16_bf16 v[234:249], v[214:217], v[126:129], v[234:249]
	s_cmp_le_i32 s26, s27
	s_cbranch_scc1 .Lff2a_z2
	v_cmp_le_i32_e32 vcc, v165, v195
	s_nop 8
	v_cndmask_b32_e32 v234, v155, v234, vcc
	v_cmp_lt_i32_e32 vcc, v163, v195
	s_nop 1
	v_cndmask_b32_e32 v219, v155, v219, vcc
	v_cmp_le_i32_e32 vcc, v163, v195
	s_nop 1
	v_cndmask_b32_e32 v218, v155, v218, vcc
	v_cmp_le_i32_e32 vcc, v166, v195
	s_nop 1
	v_cndmask_b32_e32 v235, v155, v235, vcc
	v_cmp_le_i32_e32 vcc, v167, v195
	s_nop 1
	v_cndmask_b32_e32 v220, v155, v220, vcc
	v_cmp_le_i32_e32 vcc, v168, v195
	s_nop 1
	v_cndmask_b32_e32 v236, v155, v236, vcc
	v_cmp_le_i32_e32 vcc, v169, v195
	s_nop 1
	v_cndmask_b32_e32 v221, v155, v221, vcc
	v_cmp_le_i32_e32 vcc, v170, v195
	s_nop 1
	v_cndmask_b32_e32 v237, v155, v237, vcc
	v_cmp_le_i32_e32 vcc, v171, v195
	s_nop 1
	v_cndmask_b32_e32 v222, v155, v222, vcc
	v_cmp_le_i32_e32 vcc, v172, v195
	s_nop 1
	v_cndmask_b32_e32 v238, v155, v238, vcc
	v_cmp_le_i32_e32 vcc, v173, v195
	s_nop 1
	v_cndmask_b32_e32 v223, v155, v223, vcc
	v_cmp_le_i32_e32 vcc, v174, v195
	s_nop 1
	v_cndmask_b32_e32 v239, v155, v239, vcc
	v_cmp_le_i32_e32 vcc, v175, v195
	s_nop 1
	v_cndmask_b32_e32 v224, v155, v224, vcc
	v_cmp_le_i32_e32 vcc, v176, v195
	s_nop 1
	v_cndmask_b32_e32 v240, v155, v240, vcc
	v_cmp_le_i32_e32 vcc, v177, v195
	s_nop 1
	v_cndmask_b32_e32 v225, v155, v225, vcc
	v_cmp_le_i32_e32 vcc, v178, v195
	s_nop 1
	v_cndmask_b32_e32 v241, v155, v241, vcc
	v_cmp_le_i32_e32 vcc, v179, v195
	s_nop 1
	v_cndmask_b32_e32 v226, v155, v226, vcc
	v_cmp_le_i32_e32 vcc, v180, v195
	s_nop 1
	v_cndmask_b32_e32 v242, v155, v242, vcc
	v_cmp_le_i32_e32 vcc, v181, v195
	s_nop 1
	v_cndmask_b32_e32 v227, v155, v227, vcc
	v_cmp_le_i32_e32 vcc, v182, v195
	s_nop 1
	v_cndmask_b32_e32 v243, v155, v243, vcc
	v_cmp_le_i32_e32 vcc, v183, v195
	s_nop 1
	v_cndmask_b32_e32 v228, v155, v228, vcc
	v_cmp_le_i32_e32 vcc, v184, v195
	s_nop 1
	v_cndmask_b32_e32 v244, v155, v244, vcc
	v_cmp_le_i32_e32 vcc, v185, v195
	s_nop 1
	v_cndmask_b32_e32 v229, v155, v229, vcc
	v_cmp_le_i32_e32 vcc, v186, v195
	s_nop 1
	v_cndmask_b32_e32 v245, v155, v245, vcc
	v_cmp_le_i32_e32 vcc, v187, v195
	s_nop 1
	v_cndmask_b32_e32 v230, v155, v230, vcc
	v_cmp_le_i32_e32 vcc, v188, v195
	s_nop 1
	v_cndmask_b32_e32 v246, v155, v246, vcc
	v_cmp_le_i32_e32 vcc, v189, v195
	s_nop 1
	v_cndmask_b32_e32 v231, v155, v231, vcc
	v_cmp_le_i32_e32 vcc, v190, v195
	s_nop 1
	v_cndmask_b32_e32 v247, v155, v247, vcc
	v_cmp_le_i32_e32 vcc, v191, v195
	s_nop 1
	v_cndmask_b32_e32 v232, v155, v232, vcc
	v_cmp_le_i32_e32 vcc, v192, v195
	s_nop 1
	v_cndmask_b32_e32 v248, v155, v248, vcc
	v_cmp_le_i32_e32 vcc, v193, v195
	s_nop 1
	v_cndmask_b32_e32 v233, v155, v233, vcc
	v_cmp_le_i32_e32 vcc, v194, v195
	s_nop 1
	v_cndmask_b32_e32 v249, v155, v249, vcc

.Lff2b_top:
	s_add_i32 s7, s25, -2
	s_and_b32 s7, s7, 1
	s_xor_b32 s20, s7, 1
	s_mul_i32 s21, s20, 0x4400
	s_add_i32 s21, s21, 0
	s_mulk_i32 s20, 0xc00
	s_add_i32 s20, s21, s20
	v_add3_u32 v0, s21, v149, v156
	s_waitcnt vmcnt(3)
	ds_write_b128 v0, v[130:133]
	v_add3_u32 v0, s68, v157, v156
	s_waitcnt vmcnt(2)
	ds_write_b128 v0, v[134:137] offset:34816
	v_add3_u32 v0, s21, v158, v159
	s_cmp_lt_u32 s25, s23
	s_waitcnt vmcnt(1)
	ds_write_b128 v0, v[138:141]
	v_add3_u32 v0, s68, v160, v159
	s_cselect_b32 s20, s25, s33
	s_lshl_b32 s20, s20, 20
	s_add_u32 s80, s78, s20
	s_addc_u32 s81, s79, 0
	s_add_u32 s80, s80, 0x1000
	s_addc_u32 s81, s81, 0
	s_add_u32 s82, s80, 0x1000
	s_addc_u32 s83, s81, 0
	s_waitcnt vmcnt(0)
	ds_write_b128 v0, v[142:145] offset:34816
	global_load_dwordx4 v[130:133], v150, s[80:81]
	global_load_dwordx4 v[134:137], v150, s[82:83]
	s_sub_i32 s20, s26, 63
	s_cmp_gt_i32 s20, s27
	global_load_dwordx4 v[138:141], v152, s[80:81]
	global_load_dwordx4 v[142:145], v152, s[82:83]
	s_sub_i32 s20, s26, 63
	s_cmp_gt_i32 s20, s27
	s_cbranch_scc1 .Lff2b_inact
	s_cmp_eq_u32 s72, 0
	s_cbranch_scc1 .Lff2b_first
	s_mul_i32 s20, s7, 0x4400
	v_add_u32_e32 v0, s20, v162
	ds_read_b128 v[198:201], v0
	ds_read_b128 v[202:205], v0 offset:32
	ds_read_b128 v[206:209], v0 offset:8704
	ds_read_b128 v[210:213], v0 offset:8736
	v_add_u32_e32 v78, s24, v161
	v_add_u32_e32 v66, 0x12800, v78
	v_add_u32_e32 v67, 0x12880, v78
	v_add_u32_e32 v70, 0x12820, v78
	v_add_u32_e32 v71, 0x128a0, v78
	v_add_u32_e32 v74, 0x12840, v78
	v_add_u32_e32 v75, 0x128c0, v78
	v_add_u32_e32 v79, 0x12860, v78
	v_add_u32_e32 v78, 0x128e0, v78
	ds_read_b128 v[82:85], v66
	ds_read_b128 v[66:69], v67
	ds_read_b128 v[86:89], v70
	ds_read_b128 v[70:73], v71
	ds_read_b128 v[90:93], v74
	ds_read_b128 v[74:77], v75
	ds_read_b128 v[94:97], v79
	ds_read_b128 v[78:81], v78
	s_waitcnt lgkmcnt(1)
	v_mfma_f32_32x32x16_bf16 v[82:97], v[198:201], v[98:101], v[82:97]
	v_sub_f32_e32 v218, v218, v197
	v_sub_f32_e32 v219, v219, v197
	v_sub_f32_e32 v220, v220, v197
	v_sub_f32_e32 v221, v221, v197
	v_exp_f32_e32 v218, v218
	v_exp_f32_e32 v219, v219
	v_exp_f32_e32 v220, v220
	v_exp_f32_e32 v221, v221
	s_waitcnt lgkmcnt(0)
	v_mfma_f32_32x32x16_bf16 v[66:81], v[206:209], v[98:101], v[66:81]
	v_sub_f32_e32 v222, v222, v197
	v_sub_f32_e32 v223, v223, v197
	v_sub_f32_e32 v224, v224, v197
	v_sub_f32_e32 v225, v225, v197
	v_exp_f32_e32 v222, v222
	v_exp_f32_e32 v223, v223
	v_exp_f32_e32 v224, v224
	v_exp_f32_e32 v225, v225
	v_mfma_f32_32x32x16_bf16 v[82:97], v[202:205], v[102:105], v[82:97]
	v_sub_f32_e32 v234, v234, v197
	v_sub_f32_e32 v235, v235, v197
	v_sub_f32_e32 v236, v236, v197
	v_sub_f32_e32 v237, v237, v197
	v_exp_f32_e32 v234, v234
	v_exp_f32_e32 v235, v235
	v_exp_f32_e32 v236, v236
	v_exp_f32_e32 v237, v237
	ds_read_b128 v[198:201], v0 offset:64
	ds_read_b128 v[202:205], v0 offset:96
	ds_read_b128 v[206:209], v0 offset:8768
	ds_read_b128 v[214:217], v0 offset:8800
	v_mfma_f32_32x32x16_bf16 v[66:81], v[210:213], v[102:105], v[66:81]
	v_add_f32_e32 v250, v218, v222
	v_add_f32_e32 v251, v219, v223
	v_add_f32_e32 v252, v220, v224
	v_add_f32_e32 v253, v221, v225
	v_sub_f32_e32 v238, v238, v197
	v_sub_f32_e32 v239, v239, v197
	v_sub_f32_e32 v240, v240, v197
	v_sub_f32_e32 v241, v241, v197
	s_waitcnt lgkmcnt(3)
	v_mfma_f32_32x32x16_bf16 v[82:97], v[198:201], v[106:109], v[82:97]
	v_exp_f32_e32 v238, v238
	v_exp_f32_e32 v239, v239
	v_exp_f32_e32 v240, v240
	v_exp_f32_e32 v241, v241
	v_add_f32_e32 v250, v250, v234
	v_add_f32_e32 v251, v251, v235
	v_add_f32_e32 v252, v252, v236
	v_add_f32_e32 v253, v253, v237
	s_waitcnt lgkmcnt(1)
	v_mfma_f32_32x32x16_bf16 v[66:81], v[206:209], v[106:109], v[66:81]
	v_sub_f32_e32 v226, v226, v197
	v_sub_f32_e32 v227, v227, v197
	v_sub_f32_e32 v228, v228, v197
	v_sub_f32_e32 v229, v229, v197
	v_exp_f32_e32 v226, v226
	v_exp_f32_e32 v227, v227
	v_exp_f32_e32 v228, v228
	v_exp_f32_e32 v229, v229
	v_mfma_f32_32x32x16_bf16 v[82:97], v[202:205], v[110:113], v[82:97]
	v_add_f32_e32 v250, v250, v238
	v_add_f32_e32 v251, v251, v239
	v_add_f32_e32 v252, v252, v240
	v_add_f32_e32 v253, v253, v241
	v_sub_f32_e32 v230, v230, v197
	v_sub_f32_e32 v231, v231, v197
	v_sub_f32_e32 v232, v232, v197
	v_sub_f32_e32 v233, v233, v197
	ds_read_b128 v[198:201], v0 offset:128
	ds_read_b128 v[202:205], v0 offset:160
	ds_read_b128 v[206:209], v0 offset:8832
	ds_read_b128 v[210:213], v0 offset:8864
	s_waitcnt lgkmcnt(4)
	v_mfma_f32_32x32x16_bf16 v[66:81], v[214:217], v[110:113], v[66:81]
	v_exp_f32_e32 v230, v230
	v_exp_f32_e32 v231, v231
	v_exp_f32_e32 v232, v232
	v_exp_f32_e32 v233, v233
	v_add_f32_e32 v250, v250, v226
	v_add_f32_e32 v251, v251, v227
	v_add_f32_e32 v252, v252, v228
	v_add_f32_e32 v253, v253, v229
	s_waitcnt lgkmcnt(3)
	v_mfma_f32_32x32x16_bf16 v[82:97], v[198:201], v[114:117], v[82:97]
	v_sub_f32_e32 v242, v242, v197
	v_sub_f32_e32 v243, v243, v197
	v_sub_f32_e32 v244, v244, v197
	v_sub_f32_e32 v245, v245, v197
	v_exp_f32_e32 v242, v242
	v_exp_f32_e32 v243, v243
	v_exp_f32_e32 v244, v244
	v_exp_f32_e32 v245, v245
	s_waitcnt lgkmcnt(1)
	v_mfma_f32_32x32x16_bf16 v[66:81], v[206:209], v[114:117], v[66:81]
	v_add_f32_e32 v250, v250, v230
	v_add_f32_e32 v251, v251, v231
	v_add_f32_e32 v252, v252, v232
	v_add_f32_e32 v253, v253, v233
	v_sub_f32_e32 v246, v246, v197
	v_sub_f32_e32 v247, v247, v197
	v_sub_f32_e32 v248, v248, v197
	v_sub_f32_e32 v249, v249, v197
	v_mfma_f32_32x32x16_bf16 v[82:97], v[202:205], v[118:121], v[82:97]
	v_exp_f32_e32 v246, v246
	v_exp_f32_e32 v247, v247
	v_exp_f32_e32 v248, v248
	v_exp_f32_e32 v249, v249
	v_add_f32_e32 v250, v250, v242
	v_add_f32_e32 v251, v251, v243
	v_add_f32_e32 v252, v252, v244
	v_add_f32_e32 v253, v253, v245
	ds_read_b128 v[198:201], v0 offset:192
	ds_read_b128 v[202:205], v0 offset:224
	ds_read_b128 v[206:209], v0 offset:8896
	ds_read_b128 v[214:217], v0 offset:8928
	s_waitcnt lgkmcnt(4)
	v_mfma_f32_32x32x16_bf16 v[66:81], v[210:213], v[118:121], v[66:81]
	v_add_f32_e32 v250, v250, v246
	v_add_f32_e32 v251, v251, v247
	v_add_f32_e32 v252, v252, v248
	v_add_f32_e32 v253, v253, v249
	v_add_f32_e32 v250, v250, v251
	v_add_f32_e32 v252, v252, v253
	v_add_f32_e32 v250, v250, v252
	v_add_f32_e32 v196, v196, v250
	s_waitcnt lgkmcnt(3)
	v_mfma_f32_32x32x16_bf16 v[82:97], v[198:201], v[122:125], v[82:97]
	v_cvt_pk_bf16_f32 v241, v240, v241
	v_cvt_pk_bf16_f32 v240, v238, v239
	v_cvt_pk_bf16_f32 v239, v236, v237
	v_cvt_pk_bf16_f32 v238, v234, v235
	v_cvt_pk_bf16_f32 v234, v218, v219
	v_cvt_pk_bf16_f32 v235, v220, v221
	v_cvt_pk_bf16_f32 v236, v222, v223
	v_cvt_pk_bf16_f32 v237, v224, v225
	s_waitcnt lgkmcnt(1)
	v_mfma_f32_32x32x16_bf16 v[66:81], v[206:209], v[122:125], v[66:81]
	v_cvt_pk_bf16_f32 v249, v248, v249
	v_cvt_pk_bf16_f32 v248, v246, v247
	v_cvt_pk_bf16_f32 v247, v244, v245
	v_cvt_pk_bf16_f32 v246, v242, v243
	v_cvt_pk_bf16_f32 v242, v226, v227
	v_cvt_pk_bf16_f32 v243, v228, v229
	v_cvt_pk_bf16_f32 v244, v230, v231
	v_cvt_pk_bf16_f32 v245, v232, v233
	v_mfma_f32_32x32x16_bf16 v[82:97], v[202:205], v[126:129], v[82:97]
	s_waitcnt lgkmcnt(0)
	v_mfma_f32_32x32x16_bf16 v[66:81], v[214:217], v[126:129], v[66:81]
	s_cmp_le_i32 s26, s27
	s_cbranch_scc1 .Lff2b_z2
	v_cmp_le_i32_e32 vcc, v165, v195
	s_nop 8
	v_cndmask_b32_e32 v66, v155, v66, vcc
	v_cmp_lt_i32_e32 vcc, v163, v195
	s_nop 1
	v_cndmask_b32_e32 v83, v155, v83, vcc
	v_cmp_le_i32_e32 vcc, v163, v195
	s_nop 1
	v_cndmask_b32_e32 v82, v155, v82, vcc
	v_cmp_le_i32_e32 vcc, v166, v195
	s_nop 1
	v_cndmask_b32_e32 v67, v155, v67, vcc
	v_cmp_le_i32_e32 vcc, v167, v195
	s_nop 1
	v_cndmask_b32_e32 v84, v155, v84, vcc
	v_cmp_le_i32_e32 vcc, v168, v195
	s_nop 1
	v_cndmask_b32_e32 v68, v155, v68, vcc
	v_cmp_le_i32_e32 vcc, v169, v195
	s_nop 1
	v_cndmask_b32_e32 v85, v155, v85, vcc
	v_cmp_le_i32_e32 vcc, v170, v195
	s_nop 1
	v_cndmask_b32_e32 v69, v155, v69, vcc
	v_cmp_le_i32_e32 vcc, v171, v195
	s_nop 1
	v_cndmask_b32_e32 v86, v155, v86, vcc
	v_cmp_le_i32_e32 vcc, v172, v195
	s_nop 1
	v_cndmask_b32_e32 v70, v155, v70, vcc
	v_cmp_le_i32_e32 vcc, v173, v195
	s_nop 1
	v_cndmask_b32_e32 v87, v155, v87, vcc
	v_cmp_le_i32_e32 vcc, v174, v195
	s_nop 1
	v_cndmask_b32_e32 v71, v155, v71, vcc
	v_cmp_le_i32_e32 vcc, v175, v195
	s_nop 1
	v_cndmask_b32_e32 v88, v155, v88, vcc
	v_cmp_le_i32_e32 vcc, v176, v195
	s_nop 1
	v_cndmask_b32_e32 v72, v155, v72, vcc
	v_cmp_le_i32_e32 vcc, v177, v195
	s_nop 1
	v_cndmask_b32_e32 v89, v155, v89, vcc
	v_cmp_le_i32_e32 vcc, v178, v195
	s_nop 1
	v_cndmask_b32_e32 v73, v155, v73, vcc
	v_cmp_le_i32_e32 vcc, v179, v195
	s_nop 1
	v_cndmask_b32_e32 v90, v155, v90, vcc
	v_cmp_le_i32_e32 vcc, v180, v195
	s_nop 1
	v_cndmask_b32_e32 v74, v155, v74, vcc
	v_cmp_le_i32_e32 vcc, v181, v195
	s_nop 1
	v_cndmask_b32_e32 v91, v155, v91, vcc
	v_cmp_le_i32_e32 vcc, v182, v195
	s_nop 1
	v_cndmask_b32_e32 v75, v155, v75, vcc
	v_cmp_le_i32_e32 vcc, v183, v195
	s_nop 1
	v_cndmask_b32_e32 v92, v155, v92, vcc
	v_cmp_le_i32_e32 vcc, v184, v195
	s_nop 1
	v_cndmask_b32_e32 v76, v155, v76, vcc
	v_cmp_le_i32_e32 vcc, v185, v195
	s_nop 1
	v_cndmask_b32_e32 v93, v155, v93, vcc
	v_cmp_le_i32_e32 vcc, v186, v195
	s_nop 1
	v_cndmask_b32_e32 v77, v155, v77, vcc
	v_cmp_le_i32_e32 vcc, v187, v195
	s_nop 1
	v_cndmask_b32_e32 v94, v155, v94, vcc
	v_cmp_le_i32_e32 vcc, v188, v195
	s_nop 1
	v_cndmask_b32_e32 v78, v155, v78, vcc
	v_cmp_le_i32_e32 vcc, v189, v195
	s_nop 1
	v_cndmask_b32_e32 v95, v155, v95, vcc
	v_cmp_le_i32_e32 vcc, v190, v195
	s_nop 1
	v_cndmask_b32_e32 v79, v155, v79, vcc
	v_cmp_le_i32_e32 vcc, v191, v195
	s_nop 1
	v_cndmask_b32_e32 v96, v155, v96, vcc
	v_cmp_le_i32_e32 vcc, v192, v195
	s_nop 1
	v_cndmask_b32_e32 v80, v155, v80, vcc
	v_cmp_le_i32_e32 vcc, v193, v195
	s_nop 1
	v_cndmask_b32_e32 v97, v155, v97, vcc
	v_cmp_le_i32_e32 vcc, v194, v195
	s_nop 1
	v_cndmask_b32_e32 v81, v155, v81, vcc
